# GEMM K-loops: all per-MFMA-block s_setprio 1/0 flips deleted (A/B of the flips) on v29
# speedup vs baseline: 1.0052x; 1.0028x over previous
.LBB0_201:
	ds_read_b128 v[144:147], v155
	ds_read_b128 v[148:151], v155 offset:1024
	ds_read_b128 v[158:161], v155 offset:2048
	ds_read_b128 v[162:165], v155 offset:3072
	ds_read_b128 v[166:169], v156
	ds_read_b128 v[170:173], v156 offset:1024
	ds_read_b128 v[174:177], v156 offset:2048
	ds_read_b128 v[178:181], v156 offset:3072
	s_add_u32 s56, s54, 0xfffc0080
	s_addc_u32 s57, s55, -1
	s_cmp_eq_u32 s86, 12
	s_cselect_b32 s59, s11, s57
	s_cselect_b32 s58, s26, s56
	s_cselect_b32 s57, s27, s53
	s_cselect_b32 s56, s45, s47
	v_lshl_add_u64 v[214:215], s[54:55], 0, v[138:139]
	s_add_i32 m0, s63, 0xc000
	ds_read_b128 v[182:185], v157
	ds_read_b128 v[186:189], v157 offset:1024
	ds_read_b128 v[190:193], v157 offset:2048
	ds_read_b128 v[194:197], v157 offset:3072
	ds_read_b128 v[198:201], v157 offset:4096
	ds_read_b128 v[202:205], v157 offset:5120
	ds_read_b128 v[206:209], v157 offset:6144
	ds_read_b128 v[210:213], v157 offset:7168
	global_load_lds_dwordx4 v[214:215], off
	v_lshl_add_u64 v[214:215], s[54:55], 0, v[136:137]
	s_add_i32 m0, s63, 0xe000
	s_nop 0
	global_load_lds_dwordx4 v[214:215], off
	s_waitcnt vmcnt(8)
	s_waitcnt lgkmcnt(0)
	s_barrier
	s_waitcnt lgkmcnt(0)
	v_mfma_f32_16x16x32_bf16 v[124:127], v[144:147], v[182:185], v[124:127]
	v_mfma_f32_16x16x32_bf16 v[120:123], v[158:161], v[182:185], v[120:123]
	v_mfma_f32_16x16x32_bf16 v[108:111], v[144:147], v[190:193], v[108:111]
	v_mfma_f32_16x16x32_bf16 v[104:107], v[158:161], v[190:193], v[104:107]
	v_mfma_f32_16x16x32_bf16 v[92:95], v[144:147], v[198:201], v[92:95]
	v_mfma_f32_16x16x32_bf16 v[88:91], v[158:161], v[198:201], v[88:91]
	v_mfma_f32_16x16x32_bf16 v[76:79], v[144:147], v[206:209], v[76:79]
	v_mfma_f32_16x16x32_bf16 v[72:75], v[158:161], v[206:209], v[72:75]
	v_mfma_f32_16x16x32_bf16 v[124:127], v[148:151], v[186:189], v[124:127]
	v_mfma_f32_16x16x32_bf16 v[120:123], v[162:165], v[186:189], v[120:123]
	v_mfma_f32_16x16x32_bf16 v[108:111], v[148:151], v[194:197], v[108:111]
	v_mfma_f32_16x16x32_bf16 v[104:107], v[162:165], v[194:197], v[104:107]
	v_mfma_f32_16x16x32_bf16 v[92:95], v[148:151], v[202:205], v[92:95]
	v_mfma_f32_16x16x32_bf16 v[88:91], v[162:165], v[202:205], v[88:91]
	v_mfma_f32_16x16x32_bf16 v[76:79], v[148:151], v[210:213], v[76:79]
	v_mfma_f32_16x16x32_bf16 v[72:75], v[162:165], v[210:213], v[72:75]
	v_mfma_f32_16x16x32_bf16 v[116:119], v[166:169], v[182:185], v[116:119]
	v_mfma_f32_16x16x32_bf16 v[112:115], v[174:177], v[182:185], v[112:115]
	v_mfma_f32_16x16x32_bf16 v[100:103], v[166:169], v[190:193], v[100:103]
	v_mfma_f32_16x16x32_bf16 v[96:99], v[174:177], v[190:193], v[96:99]
	v_mfma_f32_16x16x32_bf16 v[84:87], v[166:169], v[198:201], v[84:87]
	v_mfma_f32_16x16x32_bf16 v[80:83], v[174:177], v[198:201], v[80:83]
	v_mfma_f32_16x16x32_bf16 v[68:71], v[166:169], v[206:209], v[68:71]
	v_mfma_f32_16x16x32_bf16 v[64:67], v[174:177], v[206:209], v[64:67]
	v_mfma_f32_16x16x32_bf16 v[116:119], v[170:173], v[186:189], v[116:119]
	v_mfma_f32_16x16x32_bf16 v[112:115], v[178:181], v[186:189], v[112:115]
	v_mfma_f32_16x16x32_bf16 v[100:103], v[170:173], v[194:197], v[100:103]
	v_mfma_f32_16x16x32_bf16 v[96:99], v[178:181], v[194:197], v[96:99]
	v_mfma_f32_16x16x32_bf16 v[84:87], v[170:173], v[202:205], v[84:87]
	v_mfma_f32_16x16x32_bf16 v[80:83], v[178:181], v[202:205], v[80:83]
	v_mfma_f32_16x16x32_bf16 v[68:71], v[170:173], v[210:213], v[68:71]
	v_mfma_f32_16x16x32_bf16 v[64:67], v[178:181], v[210:213], v[64:67]
	s_barrier
	s_add_i32 s70, s83, s60
	v_lshl_add_u64 v[214:215], s[56:57], 0, v[130:131]
	s_mov_b32 m0, s70
	ds_read_b128 v[182:185], v157 offset:16384
	ds_read_b128 v[186:189], v157 offset:17408
	ds_read_b128 v[190:193], v157 offset:18432
	ds_read_b128 v[194:197], v157 offset:19456
	ds_read_b128 v[198:201], v157 offset:20480
	ds_read_b128 v[202:205], v157 offset:21504
	ds_read_b128 v[206:209], v157 offset:22528
	ds_read_b128 v[210:213], v157 offset:23552
	global_load_lds_dwordx4 v[214:215], off
	s_add_i32 m0, s70, 0x2000
	s_add_u32 s88, s56, 0x40000
	v_lshl_add_u64 v[216:217], s[56:57], 0, v[134:135]
	s_addc_u32 s89, s57, 0
	s_add_i32 s70, s84, s60
	global_load_lds_dwordx4 v[216:217], off
	v_lshl_add_u64 v[218:219], s[88:89], 0, v[130:131]
	s_mov_b32 m0, s70
	v_lshl_add_u64 v[220:221], s[58:59], 0, v[132:133]
	global_load_lds_dwordx4 v[218:219], off
	v_lshl_add_u64 v[218:219], s[88:89], 0, v[134:135]
	s_add_i32 m0, s70, 0x2000
	s_nop 0
	global_load_lds_dwordx4 v[218:219], off
	v_lshl_add_u64 v[218:219], s[58:59], 0, v[128:129]
	s_mov_b32 m0, s63
	s_nop 0
	global_load_lds_dwordx4 v[218:219], off
	s_mov_b32 m0, s67
	s_nop 0
	global_load_lds_dwordx4 v[220:221], off
	s_waitcnt vmcnt(8)
	s_waitcnt lgkmcnt(0)
	s_barrier
	s_waitcnt lgkmcnt(0)
	v_mfma_f32_16x16x32_bf16 v[60:63], v[144:147], v[182:185], v[60:63]
	v_mfma_f32_16x16x32_bf16 v[56:59], v[158:161], v[182:185], v[56:59]
	v_mfma_f32_16x16x32_bf16 v[44:47], v[144:147], v[190:193], v[44:47]
	v_mfma_f32_16x16x32_bf16 v[40:43], v[158:161], v[190:193], v[40:43]
	v_mfma_f32_16x16x32_bf16 v[28:31], v[144:147], v[198:201], v[28:31]
	v_mfma_f32_16x16x32_bf16 v[24:27], v[158:161], v[198:201], v[24:27]
	v_mfma_f32_16x16x32_bf16 v[12:15], v[144:147], v[206:209], v[12:15]
	v_mfma_f32_16x16x32_bf16 v[8:11], v[158:161], v[206:209], v[8:11]
	v_mfma_f32_16x16x32_bf16 v[60:63], v[148:151], v[186:189], v[60:63]
	v_mfma_f32_16x16x32_bf16 v[56:59], v[162:165], v[186:189], v[56:59]
	v_mfma_f32_16x16x32_bf16 v[44:47], v[148:151], v[194:197], v[44:47]
	v_mfma_f32_16x16x32_bf16 v[40:43], v[162:165], v[194:197], v[40:43]
	v_mfma_f32_16x16x32_bf16 v[28:31], v[148:151], v[202:205], v[28:31]
	v_mfma_f32_16x16x32_bf16 v[24:27], v[162:165], v[202:205], v[24:27]
	v_mfma_f32_16x16x32_bf16 v[12:15], v[148:151], v[210:213], v[12:15]
	v_mfma_f32_16x16x32_bf16 v[8:11], v[162:165], v[210:213], v[8:11]
	v_mfma_f32_16x16x32_bf16 v[52:55], v[166:169], v[182:185], v[52:55]
	v_mfma_f32_16x16x32_bf16 v[48:51], v[174:177], v[182:185], v[48:51]
	v_mfma_f32_16x16x32_bf16 v[36:39], v[166:169], v[190:193], v[36:39]
	v_mfma_f32_16x16x32_bf16 v[32:35], v[174:177], v[190:193], v[32:35]
	v_mfma_f32_16x16x32_bf16 v[20:23], v[166:169], v[198:201], v[20:23]
	v_mfma_f32_16x16x32_bf16 v[16:19], v[174:177], v[198:201], v[16:19]
	v_mfma_f32_16x16x32_bf16 v[4:7], v[166:169], v[206:209], v[4:7]
	v_mfma_f32_16x16x32_bf16 v[0:3], v[174:177], v[206:209], v[0:3]
	v_mfma_f32_16x16x32_bf16 v[52:55], v[170:173], v[186:189], v[52:55]
	v_mfma_f32_16x16x32_bf16 v[48:51], v[178:181], v[186:189], v[48:51]
	v_mfma_f32_16x16x32_bf16 v[36:39], v[170:173], v[194:197], v[36:39]
	v_mfma_f32_16x16x32_bf16 v[32:35], v[178:181], v[194:197], v[32:35]
	v_mfma_f32_16x16x32_bf16 v[20:23], v[170:173], v[202:205], v[20:23]
	v_mfma_f32_16x16x32_bf16 v[16:19], v[178:181], v[202:205], v[16:19]
	v_mfma_f32_16x16x32_bf16 v[4:7], v[170:173], v[210:213], v[4:7]
	v_mfma_f32_16x16x32_bf16 v[0:3], v[178:181], v[210:213], v[0:3]
	s_barrier
	s_add_i32 s70, 0, 0x18000
	s_add_i32 s87, 0, 0x1c000
	v_add_u32_e32 v162, s70, v154
	v_add_u32_e32 v178, s87, v154
	ds_read_b128 v[144:147], v162
	ds_read_b128 v[148:151], v162 offset:1024
	ds_read_b128 v[158:161], v162 offset:2048
	ds_read_b128 v[162:165], v162 offset:3072
	ds_read_b128 v[166:169], v178
	ds_read_b128 v[170:173], v178 offset:1024
	ds_read_b128 v[174:177], v178 offset:2048
	ds_read_b128 v[178:181], v178 offset:3072
	s_add_u32 s58, s58, 0x40000
	s_addc_u32 s59, s59, 0
	s_mov_b32 m0, s68
	v_lshl_add_u64 v[222:223], s[58:59], 0, v[128:129]
	ds_read_b128 v[182:185], v157 offset:32768
	ds_read_b128 v[186:189], v157 offset:33792
	ds_read_b128 v[190:193], v157 offset:34816
	ds_read_b128 v[194:197], v157 offset:35840
	ds_read_b128 v[198:201], v157 offset:36864
	ds_read_b128 v[202:205], v157 offset:37888
	ds_read_b128 v[206:209], v157 offset:38912
	ds_read_b128 v[210:213], v157 offset:39936
	global_load_lds_dwordx4 v[222:223], off
	v_lshl_add_u64 v[222:223], s[58:59], 0, v[132:133]
	s_mov_b32 m0, s69
	s_nop 0
	global_load_lds_dwordx4 v[222:223], off
	s_waitcnt vmcnt(8)
	s_waitcnt lgkmcnt(0)
	s_barrier
	s_waitcnt lgkmcnt(0)
	v_mfma_f32_16x16x32_bf16 v[124:127], v[144:147], v[182:185], v[124:127]
	v_mfma_f32_16x16x32_bf16 v[120:123], v[158:161], v[182:185], v[120:123]
	v_mfma_f32_16x16x32_bf16 v[108:111], v[144:147], v[190:193], v[108:111]
	v_mfma_f32_16x16x32_bf16 v[104:107], v[158:161], v[190:193], v[104:107]
	v_mfma_f32_16x16x32_bf16 v[92:95], v[144:147], v[198:201], v[92:95]
	v_mfma_f32_16x16x32_bf16 v[88:91], v[158:161], v[198:201], v[88:91]
	v_mfma_f32_16x16x32_bf16 v[76:79], v[144:147], v[206:209], v[76:79]
	v_mfma_f32_16x16x32_bf16 v[72:75], v[158:161], v[206:209], v[72:75]
	v_mfma_f32_16x16x32_bf16 v[124:127], v[148:151], v[186:189], v[124:127]
	v_mfma_f32_16x16x32_bf16 v[120:123], v[162:165], v[186:189], v[120:123]
	v_mfma_f32_16x16x32_bf16 v[108:111], v[148:151], v[194:197], v[108:111]
	v_mfma_f32_16x16x32_bf16 v[104:107], v[162:165], v[194:197], v[104:107]
	v_mfma_f32_16x16x32_bf16 v[92:95], v[148:151], v[202:205], v[92:95]
	v_mfma_f32_16x16x32_bf16 v[88:91], v[162:165], v[202:205], v[88:91]
	v_mfma_f32_16x16x32_bf16 v[76:79], v[148:151], v[210:213], v[76:79]
	v_mfma_f32_16x16x32_bf16 v[72:75], v[162:165], v[210:213], v[72:75]
	v_mfma_f32_16x16x32_bf16 v[116:119], v[166:169], v[182:185], v[116:119]
	v_mfma_f32_16x16x32_bf16 v[112:115], v[174:177], v[182:185], v[112:115]
	v_mfma_f32_16x16x32_bf16 v[100:103], v[166:169], v[190:193], v[100:103]
	v_mfma_f32_16x16x32_bf16 v[96:99], v[174:177], v[190:193], v[96:99]
	v_mfma_f32_16x16x32_bf16 v[84:87], v[166:169], v[198:201], v[84:87]
	v_mfma_f32_16x16x32_bf16 v[80:83], v[174:177], v[198:201], v[80:83]
	v_mfma_f32_16x16x32_bf16 v[68:71], v[166:169], v[206:209], v[68:71]
	v_mfma_f32_16x16x32_bf16 v[64:67], v[174:177], v[206:209], v[64:67]
	v_mfma_f32_16x16x32_bf16 v[116:119], v[170:173], v[186:189], v[116:119]
	v_mfma_f32_16x16x32_bf16 v[112:115], v[178:181], v[186:189], v[112:115]
	v_mfma_f32_16x16x32_bf16 v[100:103], v[170:173], v[194:197], v[100:103]
	v_mfma_f32_16x16x32_bf16 v[96:99], v[178:181], v[194:197], v[96:99]
	v_mfma_f32_16x16x32_bf16 v[84:87], v[170:173], v[202:205], v[84:87]
	v_mfma_f32_16x16x32_bf16 v[80:83], v[178:181], v[202:205], v[80:83]
	v_mfma_f32_16x16x32_bf16 v[68:71], v[170:173], v[210:213], v[68:71]
	v_mfma_f32_16x16x32_bf16 v[64:67], v[178:181], v[210:213], v[64:67]
	s_barrier
	s_add_i32 s58, s70, s60
	v_lshl_add_u64 v[214:215], v[214:215], 0, s[18:19]
	s_mov_b32 m0, s58
	ds_read_b128 v[182:185], v157 offset:49152
	ds_read_b128 v[186:189], v157 offset:50176
	ds_read_b128 v[190:193], v157 offset:51200
	ds_read_b128 v[194:197], v157 offset:52224
	ds_read_b128 v[198:201], v157 offset:53248
	ds_read_b128 v[202:205], v157 offset:54272
	ds_read_b128 v[206:209], v157 offset:55296
	ds_read_b128 v[210:213], v157 offset:56320
	global_load_lds_dwordx4 v[214:215], off
	s_add_i32 m0, s58, 0x2000
	s_add_u32 s56, s56, 0x40080
	v_lshl_add_u64 v[214:215], v[216:217], 0, s[18:19]
	s_addc_u32 s57, s57, 0
	s_add_i32 s58, s87, s60
	global_load_lds_dwordx4 v[214:215], off
	v_lshl_add_u64 v[214:215], s[56:57], 0, v[130:131]
	s_mov_b32 m0, s58
	s_nop 0
	global_load_lds_dwordx4 v[214:215], off
	v_lshl_add_u64 v[214:215], s[56:57], 0, v[134:135]
	s_add_i32 m0, s58, 0x2000
	s_nop 0
	global_load_lds_dwordx4 v[214:215], off
	v_lshl_add_u64 v[214:215], v[218:219], 0, s[18:19]
	s_mov_b32 m0, s80
	s_nop 0
	global_load_lds_dwordx4 v[214:215], off
	v_lshl_add_u64 v[214:215], v[220:221], 0, s[18:19]
	s_mov_b32 m0, s81
	s_nop 0
	global_load_lds_dwordx4 v[214:215], off
	s_waitcnt vmcnt(8)
	s_waitcnt lgkmcnt(0)
	s_barrier
	s_waitcnt lgkmcnt(0)
	v_mfma_f32_16x16x32_bf16 v[60:63], v[144:147], v[182:185], v[60:63]
	v_mfma_f32_16x16x32_bf16 v[56:59], v[158:161], v[182:185], v[56:59]
	v_mfma_f32_16x16x32_bf16 v[44:47], v[144:147], v[190:193], v[44:47]
	v_mfma_f32_16x16x32_bf16 v[40:43], v[158:161], v[190:193], v[40:43]
	v_mfma_f32_16x16x32_bf16 v[28:31], v[144:147], v[198:201], v[28:31]
	v_mfma_f32_16x16x32_bf16 v[24:27], v[158:161], v[198:201], v[24:27]
	v_mfma_f32_16x16x32_bf16 v[12:15], v[144:147], v[206:209], v[12:15]
	v_mfma_f32_16x16x32_bf16 v[8:11], v[158:161], v[206:209], v[8:11]
	v_mfma_f32_16x16x32_bf16 v[60:63], v[148:151], v[186:189], v[60:63]
	v_mfma_f32_16x16x32_bf16 v[56:59], v[162:165], v[186:189], v[56:59]
	v_mfma_f32_16x16x32_bf16 v[44:47], v[148:151], v[194:197], v[44:47]
	v_mfma_f32_16x16x32_bf16 v[40:43], v[162:165], v[194:197], v[40:43]
	v_mfma_f32_16x16x32_bf16 v[28:31], v[148:151], v[202:205], v[28:31]
	v_mfma_f32_16x16x32_bf16 v[24:27], v[162:165], v[202:205], v[24:27]
	v_mfma_f32_16x16x32_bf16 v[12:15], v[148:151], v[210:213], v[12:15]
	v_mfma_f32_16x16x32_bf16 v[8:11], v[162:165], v[210:213], v[8:11]
	v_mfma_f32_16x16x32_bf16 v[52:55], v[166:169], v[182:185], v[52:55]
	v_mfma_f32_16x16x32_bf16 v[48:51], v[174:177], v[182:185], v[48:51]
	v_mfma_f32_16x16x32_bf16 v[36:39], v[166:169], v[190:193], v[36:39]
	v_mfma_f32_16x16x32_bf16 v[32:35], v[174:177], v[190:193], v[32:35]
	v_mfma_f32_16x16x32_bf16 v[20:23], v[166:169], v[198:201], v[20:23]
	v_mfma_f32_16x16x32_bf16 v[16:19], v[174:177], v[198:201], v[16:19]
	v_mfma_f32_16x16x32_bf16 v[4:7], v[166:169], v[206:209], v[4:7]
	v_mfma_f32_16x16x32_bf16 v[0:3], v[174:177], v[206:209], v[0:3]
	v_mfma_f32_16x16x32_bf16 v[52:55], v[170:173], v[186:189], v[52:55]
	v_mfma_f32_16x16x32_bf16 v[48:51], v[178:181], v[186:189], v[48:51]
	v_mfma_f32_16x16x32_bf16 v[36:39], v[170:173], v[194:197], v[36:39]
	v_mfma_f32_16x16x32_bf16 v[32:35], v[178:181], v[194:197], v[32:35]
	v_mfma_f32_16x16x32_bf16 v[20:23], v[170:173], v[202:205], v[20:23]
	v_mfma_f32_16x16x32_bf16 v[16:19], v[178:181], v[202:205], v[16:19]
	v_mfma_f32_16x16x32_bf16 v[4:7], v[170:173], v[210:213], v[4:7]
	v_mfma_f32_16x16x32_bf16 v[0:3], v[178:181], v[210:213], v[0:3]
	s_barrier
	s_add_i32 s86, s86, 2
	s_add_u32 s47, s47, 0x100
	s_addc_u32 s53, s53, 0
	s_add_u32 s54, s54, 0x100
	s_addc_u32 s55, s55, 0
	s_cmp_gt_u32 s86, 13
	s_cbranch_scc0 .LBB0_201
	s_and_b64 vcc, exec, s[42:43]
	s_cbranch_vccz .LBB0_204
	s_barrier

.LBB0_733:
	ds_read_b128 v[144:147], v151
	ds_read_b128 v[154:157], v151 offset:1024
	ds_read_b128 v[158:161], v151 offset:2048
	ds_read_b128 v[162:165], v151 offset:3072
	ds_read_b128 v[166:169], v152
	ds_read_b128 v[170:173], v152 offset:1024
	ds_read_b128 v[174:177], v152 offset:2048
	ds_read_b128 v[178:181], v152 offset:3072
	s_add_u32 s22, s46, 0xfffc0080
	s_addc_u32 s23, s47, -1
	s_cmp_eq_u32 s71, 12
	s_cselect_b32 s51, s26, s23
	s_cselect_b32 s50, s27, s22
	s_cselect_b32 s49, s39, s69
	s_cselect_b32 s48, s41, s68
	v_lshl_add_u64 v[214:215], s[46:47], 0, v[138:139]
	s_add_i32 m0, s13, 0xc000
	ds_read_b128 v[182:185], v153
	ds_read_b128 v[186:189], v153 offset:1024
	ds_read_b128 v[190:193], v153 offset:2048
	ds_read_b128 v[194:197], v153 offset:3072
	ds_read_b128 v[198:201], v153 offset:4096
	ds_read_b128 v[202:205], v153 offset:5120
	ds_read_b128 v[206:209], v153 offset:6144
	ds_read_b128 v[210:213], v153 offset:7168
	global_load_lds_dwordx4 v[214:215], off
	v_lshl_add_u64 v[214:215], s[46:47], 0, v[136:137]
	s_add_i32 m0, s13, 0xe000
	s_nop 0
	global_load_lds_dwordx4 v[214:215], off
	s_waitcnt vmcnt(8)
	s_waitcnt lgkmcnt(0)
	s_barrier
	s_waitcnt lgkmcnt(0)
	v_mfma_f32_16x16x32_bf16 v[124:127], v[144:147], v[182:185], v[124:127]
	v_mfma_f32_16x16x32_bf16 v[120:123], v[158:161], v[182:185], v[120:123]
	v_mfma_f32_16x16x32_bf16 v[108:111], v[144:147], v[190:193], v[108:111]
	v_mfma_f32_16x16x32_bf16 v[104:107], v[158:161], v[190:193], v[104:107]
	v_mfma_f32_16x16x32_bf16 v[92:95], v[144:147], v[198:201], v[92:95]
	v_mfma_f32_16x16x32_bf16 v[88:91], v[158:161], v[198:201], v[88:91]
	v_mfma_f32_16x16x32_bf16 v[76:79], v[144:147], v[206:209], v[76:79]
	v_mfma_f32_16x16x32_bf16 v[72:75], v[158:161], v[206:209], v[72:75]
	v_mfma_f32_16x16x32_bf16 v[124:127], v[154:157], v[186:189], v[124:127]
	v_mfma_f32_16x16x32_bf16 v[120:123], v[162:165], v[186:189], v[120:123]
	v_mfma_f32_16x16x32_bf16 v[108:111], v[154:157], v[194:197], v[108:111]
	v_mfma_f32_16x16x32_bf16 v[104:107], v[162:165], v[194:197], v[104:107]
	v_mfma_f32_16x16x32_bf16 v[92:95], v[154:157], v[202:205], v[92:95]
	v_mfma_f32_16x16x32_bf16 v[88:91], v[162:165], v[202:205], v[88:91]
	v_mfma_f32_16x16x32_bf16 v[76:79], v[154:157], v[210:213], v[76:79]
	v_mfma_f32_16x16x32_bf16 v[72:75], v[162:165], v[210:213], v[72:75]
	v_mfma_f32_16x16x32_bf16 v[116:119], v[166:169], v[182:185], v[116:119]
	v_mfma_f32_16x16x32_bf16 v[112:115], v[174:177], v[182:185], v[112:115]
	v_mfma_f32_16x16x32_bf16 v[100:103], v[166:169], v[190:193], v[100:103]
	v_mfma_f32_16x16x32_bf16 v[96:99], v[174:177], v[190:193], v[96:99]
	v_mfma_f32_16x16x32_bf16 v[84:87], v[166:169], v[198:201], v[84:87]
	v_mfma_f32_16x16x32_bf16 v[80:83], v[174:177], v[198:201], v[80:83]
	v_mfma_f32_16x16x32_bf16 v[68:71], v[166:169], v[206:209], v[68:71]
	v_mfma_f32_16x16x32_bf16 v[64:67], v[174:177], v[206:209], v[64:67]
	v_mfma_f32_16x16x32_bf16 v[116:119], v[170:173], v[186:189], v[116:119]
	v_mfma_f32_16x16x32_bf16 v[112:115], v[178:181], v[186:189], v[112:115]
	v_mfma_f32_16x16x32_bf16 v[100:103], v[170:173], v[194:197], v[100:103]
	v_mfma_f32_16x16x32_bf16 v[96:99], v[178:181], v[194:197], v[96:99]
	v_mfma_f32_16x16x32_bf16 v[84:87], v[170:173], v[202:205], v[84:87]
	v_mfma_f32_16x16x32_bf16 v[80:83], v[178:181], v[202:205], v[80:83]
	v_mfma_f32_16x16x32_bf16 v[68:71], v[170:173], v[210:213], v[68:71]
	v_mfma_f32_16x16x32_bf16 v[64:67], v[178:181], v[210:213], v[64:67]
	s_barrier
	s_add_i32 s22, s65, s56
	v_lshl_add_u64 v[214:215], s[48:49], 0, v[130:131]
	s_mov_b32 m0, s22
	ds_read_b128 v[182:185], v153 offset:16384
	ds_read_b128 v[186:189], v153 offset:17408
	ds_read_b128 v[190:193], v153 offset:18432
	ds_read_b128 v[194:197], v153 offset:19456
	ds_read_b128 v[198:201], v153 offset:20480
	ds_read_b128 v[202:205], v153 offset:21504
	ds_read_b128 v[206:209], v153 offset:22528
	ds_read_b128 v[210:213], v153 offset:23552
	global_load_lds_dwordx4 v[214:215], off
	s_add_i32 m0, s22, 0x2000
	s_add_u32 s80, s48, 0x40000
	v_lshl_add_u64 v[216:217], s[48:49], 0, v[134:135]
	s_addc_u32 s81, s49, 0
	s_add_i32 s22, s66, s56
	global_load_lds_dwordx4 v[216:217], off
	v_lshl_add_u64 v[218:219], s[80:81], 0, v[130:131]
	s_mov_b32 m0, s22
	v_lshl_add_u64 v[220:221], s[50:51], 0, v[132:133]
	global_load_lds_dwordx4 v[218:219], off
	v_lshl_add_u64 v[218:219], s[80:81], 0, v[134:135]
	s_add_i32 m0, s22, 0x2000
	s_nop 0
	global_load_lds_dwordx4 v[218:219], off
	v_lshl_add_u64 v[218:219], s[50:51], 0, v[128:129]
	s_mov_b32 m0, s13
	s_nop 0
	global_load_lds_dwordx4 v[218:219], off
	s_mov_b32 m0, s57
	s_nop 0
	global_load_lds_dwordx4 v[220:221], off
	s_waitcnt vmcnt(8)
	s_waitcnt lgkmcnt(0)
	s_barrier
	s_waitcnt lgkmcnt(0)
	v_mfma_f32_16x16x32_bf16 v[60:63], v[144:147], v[182:185], v[60:63]
	v_mfma_f32_16x16x32_bf16 v[56:59], v[158:161], v[182:185], v[56:59]
	v_mfma_f32_16x16x32_bf16 v[44:47], v[144:147], v[190:193], v[44:47]
	v_mfma_f32_16x16x32_bf16 v[40:43], v[158:161], v[190:193], v[40:43]
	v_mfma_f32_16x16x32_bf16 v[28:31], v[144:147], v[198:201], v[28:31]
	v_mfma_f32_16x16x32_bf16 v[24:27], v[158:161], v[198:201], v[24:27]
	v_mfma_f32_16x16x32_bf16 v[12:15], v[144:147], v[206:209], v[12:15]
	v_mfma_f32_16x16x32_bf16 v[8:11], v[158:161], v[206:209], v[8:11]
	v_mfma_f32_16x16x32_bf16 v[60:63], v[154:157], v[186:189], v[60:63]
	v_mfma_f32_16x16x32_bf16 v[56:59], v[162:165], v[186:189], v[56:59]
	v_mfma_f32_16x16x32_bf16 v[44:47], v[154:157], v[194:197], v[44:47]
	v_mfma_f32_16x16x32_bf16 v[40:43], v[162:165], v[194:197], v[40:43]
	v_mfma_f32_16x16x32_bf16 v[28:31], v[154:157], v[202:205], v[28:31]
	v_mfma_f32_16x16x32_bf16 v[24:27], v[162:165], v[202:205], v[24:27]
	v_mfma_f32_16x16x32_bf16 v[12:15], v[154:157], v[210:213], v[12:15]
	v_mfma_f32_16x16x32_bf16 v[8:11], v[162:165], v[210:213], v[8:11]
	v_mfma_f32_16x16x32_bf16 v[52:55], v[166:169], v[182:185], v[52:55]
	v_mfma_f32_16x16x32_bf16 v[48:51], v[174:177], v[182:185], v[48:51]
	v_mfma_f32_16x16x32_bf16 v[36:39], v[166:169], v[190:193], v[36:39]
	v_mfma_f32_16x16x32_bf16 v[32:35], v[174:177], v[190:193], v[32:35]
	v_mfma_f32_16x16x32_bf16 v[20:23], v[166:169], v[198:201], v[20:23]
	v_mfma_f32_16x16x32_bf16 v[16:19], v[174:177], v[198:201], v[16:19]
	v_mfma_f32_16x16x32_bf16 v[4:7], v[166:169], v[206:209], v[4:7]
	v_mfma_f32_16x16x32_bf16 v[0:3], v[174:177], v[206:209], v[0:3]
	v_mfma_f32_16x16x32_bf16 v[52:55], v[170:173], v[186:189], v[52:55]
	v_mfma_f32_16x16x32_bf16 v[48:51], v[178:181], v[186:189], v[48:51]
	v_mfma_f32_16x16x32_bf16 v[36:39], v[170:173], v[194:197], v[36:39]
	v_mfma_f32_16x16x32_bf16 v[32:35], v[178:181], v[194:197], v[32:35]
	v_mfma_f32_16x16x32_bf16 v[20:23], v[170:173], v[202:205], v[20:23]
	v_mfma_f32_16x16x32_bf16 v[16:19], v[178:181], v[202:205], v[16:19]
	v_mfma_f32_16x16x32_bf16 v[4:7], v[170:173], v[210:213], v[4:7]
	v_mfma_f32_16x16x32_bf16 v[0:3], v[178:181], v[210:213], v[0:3]
	s_barrier
	s_add_i32 s22, 0, 0x18000
	s_add_i32 s23, 0, 0x1c000
	v_add_u32_e32 v162, s22, v150
	v_add_u32_e32 v178, s23, v150
	ds_read_b128 v[144:147], v162
	ds_read_b128 v[154:157], v162 offset:1024
	ds_read_b128 v[158:161], v162 offset:2048
	ds_read_b128 v[162:165], v162 offset:3072
	ds_read_b128 v[166:169], v178
	ds_read_b128 v[170:173], v178 offset:1024
	ds_read_b128 v[174:177], v178 offset:2048
	ds_read_b128 v[178:181], v178 offset:3072
	s_add_u32 s50, s50, 0x40000
	s_addc_u32 s51, s51, 0
	s_mov_b32 m0, s58
	v_lshl_add_u64 v[222:223], s[50:51], 0, v[128:129]
	ds_read_b128 v[182:185], v153 offset:32768
	ds_read_b128 v[186:189], v153 offset:33792
	ds_read_b128 v[190:193], v153 offset:34816
	ds_read_b128 v[194:197], v153 offset:35840
	ds_read_b128 v[198:201], v153 offset:36864
	ds_read_b128 v[202:205], v153 offset:37888
	ds_read_b128 v[206:209], v153 offset:38912
	ds_read_b128 v[210:213], v153 offset:39936
	global_load_lds_dwordx4 v[222:223], off
	v_lshl_add_u64 v[222:223], s[50:51], 0, v[132:133]
	s_mov_b32 m0, s59
	s_nop 0
	global_load_lds_dwordx4 v[222:223], off
	s_waitcnt vmcnt(8)
	s_waitcnt lgkmcnt(0)
	s_barrier
	s_waitcnt lgkmcnt(0)
	v_mfma_f32_16x16x32_bf16 v[124:127], v[144:147], v[182:185], v[124:127]
	v_mfma_f32_16x16x32_bf16 v[120:123], v[158:161], v[182:185], v[120:123]
	v_mfma_f32_16x16x32_bf16 v[108:111], v[144:147], v[190:193], v[108:111]
	v_mfma_f32_16x16x32_bf16 v[104:107], v[158:161], v[190:193], v[104:107]
	v_mfma_f32_16x16x32_bf16 v[92:95], v[144:147], v[198:201], v[92:95]
	v_mfma_f32_16x16x32_bf16 v[88:91], v[158:161], v[198:201], v[88:91]
	v_mfma_f32_16x16x32_bf16 v[76:79], v[144:147], v[206:209], v[76:79]
	v_mfma_f32_16x16x32_bf16 v[72:75], v[158:161], v[206:209], v[72:75]
	v_mfma_f32_16x16x32_bf16 v[124:127], v[154:157], v[186:189], v[124:127]
	v_mfma_f32_16x16x32_bf16 v[120:123], v[162:165], v[186:189], v[120:123]
	v_mfma_f32_16x16x32_bf16 v[108:111], v[154:157], v[194:197], v[108:111]
	v_mfma_f32_16x16x32_bf16 v[104:107], v[162:165], v[194:197], v[104:107]
	v_mfma_f32_16x16x32_bf16 v[92:95], v[154:157], v[202:205], v[92:95]
	v_mfma_f32_16x16x32_bf16 v[88:91], v[162:165], v[202:205], v[88:91]
	v_mfma_f32_16x16x32_bf16 v[76:79], v[154:157], v[210:213], v[76:79]
	v_mfma_f32_16x16x32_bf16 v[72:75], v[162:165], v[210:213], v[72:75]
	v_mfma_f32_16x16x32_bf16 v[116:119], v[166:169], v[182:185], v[116:119]
	v_mfma_f32_16x16x32_bf16 v[112:115], v[174:177], v[182:185], v[112:115]
	v_mfma_f32_16x16x32_bf16 v[100:103], v[166:169], v[190:193], v[100:103]
	v_mfma_f32_16x16x32_bf16 v[96:99], v[174:177], v[190:193], v[96:99]
	v_mfma_f32_16x16x32_bf16 v[84:87], v[166:169], v[198:201], v[84:87]
	v_mfma_f32_16x16x32_bf16 v[80:83], v[174:177], v[198:201], v[80:83]
	v_mfma_f32_16x16x32_bf16 v[68:71], v[166:169], v[206:209], v[68:71]
	v_mfma_f32_16x16x32_bf16 v[64:67], v[174:177], v[206:209], v[64:67]
	v_mfma_f32_16x16x32_bf16 v[116:119], v[170:173], v[186:189], v[116:119]
	v_mfma_f32_16x16x32_bf16 v[112:115], v[178:181], v[186:189], v[112:115]
	v_mfma_f32_16x16x32_bf16 v[100:103], v[170:173], v[194:197], v[100:103]
	v_mfma_f32_16x16x32_bf16 v[96:99], v[178:181], v[194:197], v[96:99]
	v_mfma_f32_16x16x32_bf16 v[84:87], v[170:173], v[202:205], v[84:87]
	v_mfma_f32_16x16x32_bf16 v[80:83], v[178:181], v[202:205], v[80:83]
	v_mfma_f32_16x16x32_bf16 v[68:71], v[170:173], v[210:213], v[68:71]
	v_mfma_f32_16x16x32_bf16 v[64:67], v[178:181], v[210:213], v[64:67]
	s_barrier
	s_add_i32 s22, s22, s56
	v_lshl_add_u64 v[214:215], v[214:215], 0, s[34:35]
	s_mov_b32 m0, s22
	ds_read_b128 v[182:185], v153 offset:49152
	ds_read_b128 v[186:189], v153 offset:50176
	ds_read_b128 v[190:193], v153 offset:51200
	ds_read_b128 v[194:197], v153 offset:52224
	ds_read_b128 v[198:201], v153 offset:53248
	ds_read_b128 v[202:205], v153 offset:54272
	ds_read_b128 v[206:209], v153 offset:55296
	ds_read_b128 v[210:213], v153 offset:56320
	global_load_lds_dwordx4 v[214:215], off
	s_add_i32 m0, s22, 0x2000
	s_add_u32 s48, s48, 0x40080
	v_lshl_add_u64 v[214:215], v[216:217], 0, s[34:35]
	s_addc_u32 s49, s49, 0
	s_add_i32 s22, s23, s56
	global_load_lds_dwordx4 v[214:215], off
	v_lshl_add_u64 v[214:215], s[48:49], 0, v[130:131]
	s_mov_b32 m0, s22
	s_nop 0
	global_load_lds_dwordx4 v[214:215], off
	v_lshl_add_u64 v[214:215], s[48:49], 0, v[134:135]
	s_add_i32 m0, s22, 0x2000
	s_nop 0
	global_load_lds_dwordx4 v[214:215], off
	v_lshl_add_u64 v[214:215], v[218:219], 0, s[34:35]
	s_mov_b32 m0, s63
	s_nop 0
	global_load_lds_dwordx4 v[214:215], off
	v_lshl_add_u64 v[214:215], v[220:221], 0, s[34:35]
	s_mov_b32 m0, s64
	s_nop 0
	global_load_lds_dwordx4 v[214:215], off
	s_waitcnt vmcnt(8)
	s_waitcnt lgkmcnt(0)
	s_barrier
	s_waitcnt lgkmcnt(0)
	v_mfma_f32_16x16x32_bf16 v[60:63], v[144:147], v[182:185], v[60:63]
	v_mfma_f32_16x16x32_bf16 v[56:59], v[158:161], v[182:185], v[56:59]
	v_mfma_f32_16x16x32_bf16 v[44:47], v[144:147], v[190:193], v[44:47]
	v_mfma_f32_16x16x32_bf16 v[40:43], v[158:161], v[190:193], v[40:43]
	v_mfma_f32_16x16x32_bf16 v[28:31], v[144:147], v[198:201], v[28:31]
	v_mfma_f32_16x16x32_bf16 v[24:27], v[158:161], v[198:201], v[24:27]
	v_mfma_f32_16x16x32_bf16 v[12:15], v[144:147], v[206:209], v[12:15]
	v_mfma_f32_16x16x32_bf16 v[8:11], v[158:161], v[206:209], v[8:11]
	v_mfma_f32_16x16x32_bf16 v[60:63], v[154:157], v[186:189], v[60:63]
	v_mfma_f32_16x16x32_bf16 v[56:59], v[162:165], v[186:189], v[56:59]
	v_mfma_f32_16x16x32_bf16 v[44:47], v[154:157], v[194:197], v[44:47]
	v_mfma_f32_16x16x32_bf16 v[40:43], v[162:165], v[194:197], v[40:43]
	v_mfma_f32_16x16x32_bf16 v[28:31], v[154:157], v[202:205], v[28:31]
	v_mfma_f32_16x16x32_bf16 v[24:27], v[162:165], v[202:205], v[24:27]
	v_mfma_f32_16x16x32_bf16 v[12:15], v[154:157], v[210:213], v[12:15]
	v_mfma_f32_16x16x32_bf16 v[8:11], v[162:165], v[210:213], v[8:11]
	v_mfma_f32_16x16x32_bf16 v[52:55], v[166:169], v[182:185], v[52:55]
	v_mfma_f32_16x16x32_bf16 v[48:51], v[174:177], v[182:185], v[48:51]
	v_mfma_f32_16x16x32_bf16 v[36:39], v[166:169], v[190:193], v[36:39]
	v_mfma_f32_16x16x32_bf16 v[32:35], v[174:177], v[190:193], v[32:35]
	v_mfma_f32_16x16x32_bf16 v[20:23], v[166:169], v[198:201], v[20:23]
	v_mfma_f32_16x16x32_bf16 v[16:19], v[174:177], v[198:201], v[16:19]
	v_mfma_f32_16x16x32_bf16 v[4:7], v[166:169], v[206:209], v[4:7]
	v_mfma_f32_16x16x32_bf16 v[0:3], v[174:177], v[206:209], v[0:3]
	v_mfma_f32_16x16x32_bf16 v[52:55], v[170:173], v[186:189], v[52:55]
	v_mfma_f32_16x16x32_bf16 v[48:51], v[178:181], v[186:189], v[48:51]
	v_mfma_f32_16x16x32_bf16 v[36:39], v[170:173], v[194:197], v[36:39]
	v_mfma_f32_16x16x32_bf16 v[32:35], v[178:181], v[194:197], v[32:35]
	v_mfma_f32_16x16x32_bf16 v[20:23], v[170:173], v[202:205], v[20:23]
	v_mfma_f32_16x16x32_bf16 v[16:19], v[178:181], v[202:205], v[16:19]
	v_mfma_f32_16x16x32_bf16 v[4:7], v[170:173], v[210:213], v[4:7]
	v_mfma_f32_16x16x32_bf16 v[0:3], v[178:181], v[210:213], v[0:3]
	s_barrier
	s_add_i32 s71, s71, 2
	s_add_u32 s68, s68, 0x100
	s_addc_u32 s69, s69, 0
	s_add_u32 s46, s46, 0x100
	s_addc_u32 s47, s47, 0
	s_cmp_gt_u32 s71, 13
	s_cbranch_scc0 .LBB0_733
	s_and_b64 vcc, exec, s[36:37]
	s_cbranch_vccz .LBB0_736
	s_barrier

.LBB0_849:
	ds_read_b128 v[146:149], v227
	ds_read_b128 v[150:153], v227 offset:1024
	ds_read_b128 v[154:157], v227 offset:2048
	ds_read_b128 v[158:161], v227 offset:3072
	ds_read_b128 v[162:165], v228
	ds_read_b128 v[166:169], v228 offset:1024
	ds_read_b128 v[170:173], v228 offset:2048
	ds_read_b128 v[174:177], v228 offset:3072
	s_add_u32 s22, s12, 0xfffc2080
	s_addc_u32 s23, s13, -1
	s_cmp_eq_u32 vcc_hi, 12
	s_cselect_b32 s65, s59, s23
	s_cselect_b32 s64, s58, s22
	s_cselect_b32 s63, s27, vcc_lo
	s_cselect_b32 s62, s57, s71
	v_lshl_add_u64 v[210:211], s[12:13], 0, v[138:139]
	s_add_i32 m0, s69, 0xc000
	ds_read_b128 v[178:181], v229
	ds_read_b128 v[182:185], v229 offset:1024
	ds_read_b128 v[186:189], v229 offset:2048
	ds_read_b128 v[190:193], v229 offset:3072
	ds_read_b128 v[194:197], v229 offset:4096
	ds_read_b128 v[198:201], v229 offset:5120
	ds_read_b128 v[202:205], v229 offset:6144
	ds_read_b128 v[206:209], v229 offset:7168
	global_load_lds_dwordx4 v[210:211], off
	v_lshl_add_u64 v[210:211], s[12:13], 0, v[136:137]
	s_add_i32 m0, s69, 0xe000
	s_nop 0
	global_load_lds_dwordx4 v[210:211], off
	s_waitcnt vmcnt(8)
	s_waitcnt lgkmcnt(0)
	s_barrier
	s_waitcnt lgkmcnt(0)
	v_mfma_f32_16x16x32_bf16 v[124:127], v[146:149], v[178:181], v[124:127]
	v_mfma_f32_16x16x32_bf16 v[120:123], v[154:157], v[178:181], v[120:123]
	v_mfma_f32_16x16x32_bf16 v[116:119], v[146:149], v[186:189], v[116:119]
	v_mfma_f32_16x16x32_bf16 v[108:111], v[154:157], v[186:189], v[108:111]
	v_mfma_f32_16x16x32_bf16 v[100:103], v[146:149], v[194:197], v[100:103]
	v_mfma_f32_16x16x32_bf16 v[96:99], v[154:157], v[194:197], v[96:99]
	v_mfma_f32_16x16x32_bf16 v[84:87], v[146:149], v[202:205], v[84:87]
	v_mfma_f32_16x16x32_bf16 v[76:79], v[154:157], v[202:205], v[76:79]
	v_mfma_f32_16x16x32_bf16 v[124:127], v[150:153], v[182:185], v[124:127]
	v_mfma_f32_16x16x32_bf16 v[120:123], v[158:161], v[182:185], v[120:123]
	v_mfma_f32_16x16x32_bf16 v[116:119], v[150:153], v[190:193], v[116:119]
	v_mfma_f32_16x16x32_bf16 v[108:111], v[158:161], v[190:193], v[108:111]
	v_mfma_f32_16x16x32_bf16 v[100:103], v[150:153], v[198:201], v[100:103]
	v_mfma_f32_16x16x32_bf16 v[96:99], v[158:161], v[198:201], v[96:99]
	v_mfma_f32_16x16x32_bf16 v[84:87], v[150:153], v[206:209], v[84:87]
	v_mfma_f32_16x16x32_bf16 v[76:79], v[158:161], v[206:209], v[76:79]
	v_mfma_f32_16x16x32_bf16 v[112:115], v[162:165], v[178:181], v[112:115]
	v_mfma_f32_16x16x32_bf16 v[104:107], v[170:173], v[178:181], v[104:107]
	v_mfma_f32_16x16x32_bf16 v[92:95], v[162:165], v[186:189], v[92:95]
	v_mfma_f32_16x16x32_bf16 v[88:91], v[170:173], v[186:189], v[88:91]
	v_mfma_f32_16x16x32_bf16 v[80:83], v[162:165], v[194:197], v[80:83]
	v_mfma_f32_16x16x32_bf16 v[72:75], v[170:173], v[194:197], v[72:75]
	v_mfma_f32_16x16x32_bf16 v[68:71], v[162:165], v[202:205], v[68:71]
	v_mfma_f32_16x16x32_bf16 v[64:67], v[170:173], v[202:205], v[64:67]
	v_mfma_f32_16x16x32_bf16 v[112:115], v[166:169], v[182:185], v[112:115]
	v_mfma_f32_16x16x32_bf16 v[104:107], v[174:177], v[182:185], v[104:107]
	v_mfma_f32_16x16x32_bf16 v[92:95], v[166:169], v[190:193], v[92:95]
	v_mfma_f32_16x16x32_bf16 v[88:91], v[174:177], v[190:193], v[88:91]
	v_mfma_f32_16x16x32_bf16 v[80:83], v[166:169], v[198:201], v[80:83]
	v_mfma_f32_16x16x32_bf16 v[72:75], v[174:177], v[198:201], v[72:75]
	v_mfma_f32_16x16x32_bf16 v[68:71], v[166:169], v[206:209], v[68:71]
	v_mfma_f32_16x16x32_bf16 v[64:67], v[174:177], v[206:209], v[64:67]
	s_barrier
	s_add_i32 s22, s91, s53
	v_lshl_add_u64 v[210:211], s[62:63], 0, v[130:131]
	s_mov_b32 m0, s22
	ds_read_b128 v[178:181], v229 offset:16384
	ds_read_b128 v[182:185], v229 offset:17408
	ds_read_b128 v[186:189], v229 offset:18432
	ds_read_b128 v[190:193], v229 offset:19456
	ds_read_b128 v[194:197], v229 offset:20480
	ds_read_b128 v[198:201], v229 offset:21504
	ds_read_b128 v[202:205], v229 offset:22528
	ds_read_b128 v[206:209], v229 offset:23552
	global_load_lds_dwordx4 v[210:211], off
	s_add_i32 m0, s22, 0x2000
	s_add_u32 s22, s62, 0x40000
	v_lshl_add_u64 v[212:213], s[62:63], 0, v[134:135]
	s_addc_u32 s23, s63, 0
	s_add_i32 s70, s92, s53
	global_load_lds_dwordx4 v[212:213], off
	v_lshl_add_u64 v[214:215], s[22:23], 0, v[130:131]
	s_mov_b32 m0, s70
	v_lshl_add_u64 v[216:217], s[64:65], 0, v[132:133]
	global_load_lds_dwordx4 v[214:215], off
	v_lshl_add_u64 v[214:215], s[22:23], 0, v[134:135]
	s_add_i32 m0, s70, 0x2000
	s_nop 0
	global_load_lds_dwordx4 v[214:215], off
	v_lshl_add_u64 v[214:215], s[64:65], 0, v[128:129]
	s_mov_b32 m0, s69
	s_nop 0
	global_load_lds_dwordx4 v[214:215], off
	s_mov_b32 m0, s82
	s_nop 0
	global_load_lds_dwordx4 v[216:217], off
	s_waitcnt vmcnt(8)
	s_waitcnt lgkmcnt(0)
	s_barrier
	s_waitcnt lgkmcnt(0)
	v_mfma_f32_16x16x32_bf16 v[60:63], v[146:149], v[178:181], v[60:63]
	v_mfma_f32_16x16x32_bf16 v[56:59], v[154:157], v[178:181], v[56:59]
	v_mfma_f32_16x16x32_bf16 v[52:55], v[146:149], v[186:189], v[52:55]
	v_mfma_f32_16x16x32_bf16 v[44:47], v[154:157], v[186:189], v[44:47]
	v_mfma_f32_16x16x32_bf16 v[36:39], v[146:149], v[194:197], v[36:39]
	v_mfma_f32_16x16x32_bf16 v[32:35], v[154:157], v[194:197], v[32:35]
	v_mfma_f32_16x16x32_bf16 v[20:23], v[146:149], v[202:205], v[20:23]
	v_mfma_f32_16x16x32_bf16 v[12:15], v[154:157], v[202:205], v[12:15]
	v_mfma_f32_16x16x32_bf16 v[60:63], v[150:153], v[182:185], v[60:63]
	v_mfma_f32_16x16x32_bf16 v[56:59], v[158:161], v[182:185], v[56:59]
	v_mfma_f32_16x16x32_bf16 v[52:55], v[150:153], v[190:193], v[52:55]
	v_mfma_f32_16x16x32_bf16 v[44:47], v[158:161], v[190:193], v[44:47]
	v_mfma_f32_16x16x32_bf16 v[36:39], v[150:153], v[198:201], v[36:39]
	v_mfma_f32_16x16x32_bf16 v[32:35], v[158:161], v[198:201], v[32:35]
	v_mfma_f32_16x16x32_bf16 v[20:23], v[150:153], v[206:209], v[20:23]
	v_mfma_f32_16x16x32_bf16 v[12:15], v[158:161], v[206:209], v[12:15]
	v_mfma_f32_16x16x32_bf16 v[48:51], v[162:165], v[178:181], v[48:51]
	v_mfma_f32_16x16x32_bf16 v[40:43], v[170:173], v[178:181], v[40:43]
	v_mfma_f32_16x16x32_bf16 v[28:31], v[162:165], v[186:189], v[28:31]
	v_mfma_f32_16x16x32_bf16 v[24:27], v[170:173], v[186:189], v[24:27]
	v_mfma_f32_16x16x32_bf16 v[16:19], v[162:165], v[194:197], v[16:19]
	v_mfma_f32_16x16x32_bf16 v[8:11], v[170:173], v[194:197], v[8:11]
	v_mfma_f32_16x16x32_bf16 v[4:7], v[162:165], v[202:205], v[4:7]
	v_mfma_f32_16x16x32_bf16 v[0:3], v[170:173], v[202:205], v[0:3]
	v_mfma_f32_16x16x32_bf16 v[48:51], v[166:169], v[182:185], v[48:51]
	v_mfma_f32_16x16x32_bf16 v[40:43], v[174:177], v[182:185], v[40:43]
	v_mfma_f32_16x16x32_bf16 v[28:31], v[166:169], v[190:193], v[28:31]
	v_mfma_f32_16x16x32_bf16 v[24:27], v[174:177], v[190:193], v[24:27]
	v_mfma_f32_16x16x32_bf16 v[16:19], v[166:169], v[198:201], v[16:19]
	v_mfma_f32_16x16x32_bf16 v[8:11], v[174:177], v[198:201], v[8:11]
	v_mfma_f32_16x16x32_bf16 v[4:7], v[166:169], v[206:209], v[4:7]
	v_mfma_f32_16x16x32_bf16 v[0:3], v[174:177], v[206:209], v[0:3]
	s_barrier
	s_add_i32 s70, 0, 0x18000
	s_add_i32 s81, 0, 0x1c000
	v_add_u32_e32 v158, s70, v226
	v_add_u32_e32 v174, s81, v226
	ds_read_b128 v[146:149], v158
	ds_read_b128 v[150:153], v158 offset:1024
	ds_read_b128 v[154:157], v158 offset:2048
	ds_read_b128 v[158:161], v158 offset:3072
	ds_read_b128 v[162:165], v174
	ds_read_b128 v[166:169], v174 offset:1024
	ds_read_b128 v[170:173], v174 offset:2048
	ds_read_b128 v[174:177], v174 offset:3072
	s_add_u32 s22, s64, 0x3e000
	s_addc_u32 s23, s65, 0
	s_mov_b32 m0, s83
	v_lshl_add_u64 v[218:219], s[22:23], 0, v[128:129]
	ds_read_b128 v[178:181], v229 offset:32768
	ds_read_b128 v[182:185], v229 offset:33792
	ds_read_b128 v[186:189], v229 offset:34816
	ds_read_b128 v[190:193], v229 offset:35840
	ds_read_b128 v[194:197], v229 offset:36864
	ds_read_b128 v[198:201], v229 offset:37888
	ds_read_b128 v[202:205], v229 offset:38912
	ds_read_b128 v[206:209], v229 offset:39936
	global_load_lds_dwordx4 v[218:219], off
	v_lshl_add_u64 v[218:219], s[22:23], 0, v[132:133]
	s_mov_b32 m0, s84
	s_nop 0
	global_load_lds_dwordx4 v[218:219], off
	s_waitcnt vmcnt(8)
	s_waitcnt lgkmcnt(0)
	s_barrier
	s_waitcnt lgkmcnt(0)
	v_mfma_f32_16x16x32_bf16 v[124:127], v[146:149], v[178:181], v[124:127]
	v_mfma_f32_16x16x32_bf16 v[120:123], v[154:157], v[178:181], v[120:123]
	v_mfma_f32_16x16x32_bf16 v[116:119], v[146:149], v[186:189], v[116:119]
	v_mfma_f32_16x16x32_bf16 v[108:111], v[154:157], v[186:189], v[108:111]
	v_mfma_f32_16x16x32_bf16 v[100:103], v[146:149], v[194:197], v[100:103]
	v_mfma_f32_16x16x32_bf16 v[96:99], v[154:157], v[194:197], v[96:99]
	v_mfma_f32_16x16x32_bf16 v[84:87], v[146:149], v[202:205], v[84:87]
	v_mfma_f32_16x16x32_bf16 v[76:79], v[154:157], v[202:205], v[76:79]
	v_mfma_f32_16x16x32_bf16 v[124:127], v[150:153], v[182:185], v[124:127]
	v_mfma_f32_16x16x32_bf16 v[120:123], v[158:161], v[182:185], v[120:123]
	v_mfma_f32_16x16x32_bf16 v[116:119], v[150:153], v[190:193], v[116:119]
	v_mfma_f32_16x16x32_bf16 v[108:111], v[158:161], v[190:193], v[108:111]
	v_mfma_f32_16x16x32_bf16 v[100:103], v[150:153], v[198:201], v[100:103]
	v_mfma_f32_16x16x32_bf16 v[96:99], v[158:161], v[198:201], v[96:99]
	v_mfma_f32_16x16x32_bf16 v[84:87], v[150:153], v[206:209], v[84:87]
	v_mfma_f32_16x16x32_bf16 v[76:79], v[158:161], v[206:209], v[76:79]
	v_mfma_f32_16x16x32_bf16 v[112:115], v[162:165], v[178:181], v[112:115]
	v_mfma_f32_16x16x32_bf16 v[104:107], v[170:173], v[178:181], v[104:107]
	v_mfma_f32_16x16x32_bf16 v[92:95], v[162:165], v[186:189], v[92:95]
	v_mfma_f32_16x16x32_bf16 v[88:91], v[170:173], v[186:189], v[88:91]
	v_mfma_f32_16x16x32_bf16 v[80:83], v[162:165], v[194:197], v[80:83]
	v_mfma_f32_16x16x32_bf16 v[72:75], v[170:173], v[194:197], v[72:75]
	v_mfma_f32_16x16x32_bf16 v[68:71], v[162:165], v[202:205], v[68:71]
	v_mfma_f32_16x16x32_bf16 v[64:67], v[170:173], v[202:205], v[64:67]
	v_mfma_f32_16x16x32_bf16 v[112:115], v[166:169], v[182:185], v[112:115]
	v_mfma_f32_16x16x32_bf16 v[104:107], v[174:177], v[182:185], v[104:107]
	v_mfma_f32_16x16x32_bf16 v[92:95], v[166:169], v[190:193], v[92:95]
	v_mfma_f32_16x16x32_bf16 v[88:91], v[174:177], v[190:193], v[88:91]
	v_mfma_f32_16x16x32_bf16 v[80:83], v[166:169], v[198:201], v[80:83]
	v_mfma_f32_16x16x32_bf16 v[72:75], v[174:177], v[198:201], v[72:75]
	v_mfma_f32_16x16x32_bf16 v[68:71], v[166:169], v[206:209], v[68:71]
	v_mfma_f32_16x16x32_bf16 v[64:67], v[174:177], v[206:209], v[64:67]
	s_barrier
	s_add_i32 s22, s70, s53
	v_lshl_add_u64 v[210:211], v[210:211], 0, s[48:49]
	s_mov_b32 m0, s22
	ds_read_b128 v[178:181], v229 offset:49152
	ds_read_b128 v[182:185], v229 offset:50176
	ds_read_b128 v[186:189], v229 offset:51200
	ds_read_b128 v[190:193], v229 offset:52224
	ds_read_b128 v[194:197], v229 offset:53248
	ds_read_b128 v[198:201], v229 offset:54272
	ds_read_b128 v[202:205], v229 offset:55296
	ds_read_b128 v[206:209], v229 offset:56320
	global_load_lds_dwordx4 v[210:211], off
	s_add_i32 m0, s22, 0x2000
	s_add_u32 s22, s62, 0x40080
	v_lshl_add_u64 v[210:211], v[212:213], 0, s[48:49]
	s_addc_u32 s23, s63, 0
	s_add_i32 s62, s81, s53
	global_load_lds_dwordx4 v[210:211], off
	v_lshl_add_u64 v[210:211], s[22:23], 0, v[130:131]
	s_mov_b32 m0, s62
	s_nop 0
	global_load_lds_dwordx4 v[210:211], off
	v_lshl_add_u64 v[210:211], s[22:23], 0, v[134:135]
	s_add_i32 m0, s62, 0x2000
	s_nop 0
	global_load_lds_dwordx4 v[210:211], off
	v_lshl_add_u64 v[210:211], v[214:215], 0, s[48:49]
	s_mov_b32 m0, s86
	s_nop 0
	global_load_lds_dwordx4 v[210:211], off
	v_lshl_add_u64 v[210:211], v[216:217], 0, s[48:49]
	s_mov_b32 m0, s87
	s_nop 0
	global_load_lds_dwordx4 v[210:211], off
	s_waitcnt vmcnt(8)
	s_waitcnt lgkmcnt(0)
	s_barrier
	s_waitcnt lgkmcnt(0)
	v_mfma_f32_16x16x32_bf16 v[60:63], v[146:149], v[178:181], v[60:63]
	v_mfma_f32_16x16x32_bf16 v[56:59], v[154:157], v[178:181], v[56:59]
	v_mfma_f32_16x16x32_bf16 v[52:55], v[146:149], v[186:189], v[52:55]
	v_mfma_f32_16x16x32_bf16 v[44:47], v[154:157], v[186:189], v[44:47]
	v_mfma_f32_16x16x32_bf16 v[36:39], v[146:149], v[194:197], v[36:39]
	v_mfma_f32_16x16x32_bf16 v[32:35], v[154:157], v[194:197], v[32:35]
	v_mfma_f32_16x16x32_bf16 v[20:23], v[146:149], v[202:205], v[20:23]
	v_mfma_f32_16x16x32_bf16 v[12:15], v[154:157], v[202:205], v[12:15]
	v_mfma_f32_16x16x32_bf16 v[60:63], v[150:153], v[182:185], v[60:63]
	v_mfma_f32_16x16x32_bf16 v[56:59], v[158:161], v[182:185], v[56:59]
	v_mfma_f32_16x16x32_bf16 v[52:55], v[150:153], v[190:193], v[52:55]
	v_mfma_f32_16x16x32_bf16 v[44:47], v[158:161], v[190:193], v[44:47]
	v_mfma_f32_16x16x32_bf16 v[36:39], v[150:153], v[198:201], v[36:39]
	v_mfma_f32_16x16x32_bf16 v[32:35], v[158:161], v[198:201], v[32:35]
	v_mfma_f32_16x16x32_bf16 v[20:23], v[150:153], v[206:209], v[20:23]
	v_mfma_f32_16x16x32_bf16 v[12:15], v[158:161], v[206:209], v[12:15]
	v_mfma_f32_16x16x32_bf16 v[48:51], v[162:165], v[178:181], v[48:51]
	v_mfma_f32_16x16x32_bf16 v[40:43], v[170:173], v[178:181], v[40:43]
	v_mfma_f32_16x16x32_bf16 v[28:31], v[162:165], v[186:189], v[28:31]
	v_mfma_f32_16x16x32_bf16 v[24:27], v[170:173], v[186:189], v[24:27]
	v_mfma_f32_16x16x32_bf16 v[16:19], v[162:165], v[194:197], v[16:19]
	v_mfma_f32_16x16x32_bf16 v[8:11], v[170:173], v[194:197], v[8:11]
	v_mfma_f32_16x16x32_bf16 v[4:7], v[162:165], v[202:205], v[4:7]
	v_mfma_f32_16x16x32_bf16 v[0:3], v[170:173], v[202:205], v[0:3]
	v_mfma_f32_16x16x32_bf16 v[48:51], v[166:169], v[182:185], v[48:51]
	v_mfma_f32_16x16x32_bf16 v[40:43], v[174:177], v[182:185], v[40:43]
	v_mfma_f32_16x16x32_bf16 v[28:31], v[166:169], v[190:193], v[28:31]
	v_mfma_f32_16x16x32_bf16 v[24:27], v[174:177], v[190:193], v[24:27]
	v_mfma_f32_16x16x32_bf16 v[16:19], v[166:169], v[198:201], v[16:19]
	v_mfma_f32_16x16x32_bf16 v[8:11], v[174:177], v[198:201], v[8:11]
	v_mfma_f32_16x16x32_bf16 v[4:7], v[166:169], v[206:209], v[4:7]
	v_mfma_f32_16x16x32_bf16 v[0:3], v[174:177], v[206:209], v[0:3]
	s_barrier
	s_add_i32 vcc_hi, vcc_hi, 2
	s_add_u32 s71, s71, 0x100
	s_addc_u32 vcc_lo, vcc_lo, 0
	s_add_u32 s12, s12, 0x100
	s_addc_u32 s13, s13, 0
	s_cmp_gt_u32 vcc_hi, 13
	s_cbranch_scc0 .LBB0_849
	s_and_b64 vcc, exec, s[50:51]
	s_cbranch_vccz .LBB0_852
	s_barrier

.LBB0_1059:
	ds_read_b128 v[144:147], v151
	ds_read_b128 v[154:157], v151 offset:1024
	ds_read_b128 v[158:161], v151 offset:2048
	ds_read_b128 v[162:165], v151 offset:3072
	ds_read_b128 v[166:169], v152
	ds_read_b128 v[170:173], v152 offset:1024
	ds_read_b128 v[174:177], v152 offset:2048
	ds_read_b128 v[178:181], v152 offset:3072
	s_add_u32 s46, s44, 0x100
	s_addc_u32 s47, s45, 0
	s_cmp_eq_u32 s71, 40
	s_cselect_b32 s51, s13, s47
	s_cselect_b32 s50, s12, s46
	s_cselect_b32 s49, s43, s27
	s_cselect_b32 s48, s42, s26
	v_lshl_add_u64 v[214:215], s[44:45], 0, v[138:139]
	s_add_i32 m0, s58, 0xc000
	ds_read_b128 v[182:185], v153
	ds_read_b128 v[186:189], v153 offset:1024
	ds_read_b128 v[190:193], v153 offset:2048
	ds_read_b128 v[194:197], v153 offset:3072
	ds_read_b128 v[198:201], v153 offset:4096
	ds_read_b128 v[202:205], v153 offset:5120
	ds_read_b128 v[206:209], v153 offset:6144
	ds_read_b128 v[210:213], v153 offset:7168
	global_load_lds_dwordx4 v[214:215], off
	v_lshl_add_u64 v[214:215], s[44:45], 0, v[136:137]
	s_add_i32 m0, s58, 0xe000
	s_nop 0
	global_load_lds_dwordx4 v[214:215], off
	s_waitcnt vmcnt(8)
	s_waitcnt lgkmcnt(0)
	s_barrier
	s_waitcnt lgkmcnt(0)
	v_mfma_f32_16x16x32_bf16 v[124:127], v[144:147], v[182:185], v[124:127]
	v_mfma_f32_16x16x32_bf16 v[120:123], v[158:161], v[182:185], v[120:123]
	v_mfma_f32_16x16x32_bf16 v[108:111], v[144:147], v[190:193], v[108:111]
	v_mfma_f32_16x16x32_bf16 v[104:107], v[158:161], v[190:193], v[104:107]
	v_mfma_f32_16x16x32_bf16 v[92:95], v[144:147], v[198:201], v[92:95]
	v_mfma_f32_16x16x32_bf16 v[88:91], v[158:161], v[198:201], v[88:91]
	v_mfma_f32_16x16x32_bf16 v[76:79], v[144:147], v[206:209], v[76:79]
	v_mfma_f32_16x16x32_bf16 v[72:75], v[158:161], v[206:209], v[72:75]
	v_mfma_f32_16x16x32_bf16 v[124:127], v[154:157], v[186:189], v[124:127]
	v_mfma_f32_16x16x32_bf16 v[120:123], v[162:165], v[186:189], v[120:123]
	v_mfma_f32_16x16x32_bf16 v[108:111], v[154:157], v[194:197], v[108:111]
	v_mfma_f32_16x16x32_bf16 v[104:107], v[162:165], v[194:197], v[104:107]
	v_mfma_f32_16x16x32_bf16 v[92:95], v[154:157], v[202:205], v[92:95]
	v_mfma_f32_16x16x32_bf16 v[88:91], v[162:165], v[202:205], v[88:91]
	v_mfma_f32_16x16x32_bf16 v[76:79], v[154:157], v[210:213], v[76:79]
	v_mfma_f32_16x16x32_bf16 v[72:75], v[162:165], v[210:213], v[72:75]
	v_mfma_f32_16x16x32_bf16 v[116:119], v[166:169], v[182:185], v[116:119]
	v_mfma_f32_16x16x32_bf16 v[112:115], v[174:177], v[182:185], v[112:115]
	v_mfma_f32_16x16x32_bf16 v[100:103], v[166:169], v[190:193], v[100:103]
	v_mfma_f32_16x16x32_bf16 v[96:99], v[174:177], v[190:193], v[96:99]
	v_mfma_f32_16x16x32_bf16 v[84:87], v[166:169], v[198:201], v[84:87]
	v_mfma_f32_16x16x32_bf16 v[80:83], v[174:177], v[198:201], v[80:83]
	v_mfma_f32_16x16x32_bf16 v[68:71], v[166:169], v[206:209], v[68:71]
	v_mfma_f32_16x16x32_bf16 v[64:67], v[174:177], v[206:209], v[64:67]
	v_mfma_f32_16x16x32_bf16 v[116:119], v[170:173], v[186:189], v[116:119]
	v_mfma_f32_16x16x32_bf16 v[112:115], v[178:181], v[186:189], v[112:115]
	v_mfma_f32_16x16x32_bf16 v[100:103], v[170:173], v[194:197], v[100:103]
	v_mfma_f32_16x16x32_bf16 v[96:99], v[178:181], v[194:197], v[96:99]
	v_mfma_f32_16x16x32_bf16 v[84:87], v[170:173], v[202:205], v[84:87]
	v_mfma_f32_16x16x32_bf16 v[80:83], v[178:181], v[202:205], v[80:83]
	v_mfma_f32_16x16x32_bf16 v[68:71], v[170:173], v[210:213], v[68:71]
	v_mfma_f32_16x16x32_bf16 v[64:67], v[178:181], v[210:213], v[64:67]
	s_barrier
	s_add_i32 s22, s67, s57
	v_lshl_add_u64 v[214:215], s[48:49], 0, v[130:131]
	s_mov_b32 m0, s22
	ds_read_b128 v[182:185], v153 offset:16384
	ds_read_b128 v[186:189], v153 offset:17408
	ds_read_b128 v[190:193], v153 offset:18432
	ds_read_b128 v[194:197], v153 offset:19456
	ds_read_b128 v[198:201], v153 offset:20480
	ds_read_b128 v[202:205], v153 offset:21504
	ds_read_b128 v[206:209], v153 offset:22528
	ds_read_b128 v[210:213], v153 offset:23552
	global_load_lds_dwordx4 v[214:215], off
	s_add_i32 m0, s22, 0x2000
	s_add_u32 s22, s48, 0xb0000
	v_lshl_add_u64 v[216:217], s[48:49], 0, v[134:135]
	s_addc_u32 s23, s49, 0
	s_add_i32 s44, s68, s57
	global_load_lds_dwordx4 v[216:217], off
	v_lshl_add_u64 v[218:219], s[22:23], 0, v[130:131]
	s_mov_b32 m0, s44
	v_lshl_add_u64 v[220:221], s[50:51], 0, v[132:133]
	global_load_lds_dwordx4 v[218:219], off
	v_lshl_add_u64 v[218:219], s[22:23], 0, v[134:135]
	s_add_i32 m0, s44, 0x2000
	s_nop 0
	global_load_lds_dwordx4 v[218:219], off
	v_lshl_add_u64 v[218:219], s[50:51], 0, v[128:129]
	s_mov_b32 m0, s58
	s_nop 0
	global_load_lds_dwordx4 v[218:219], off
	s_mov_b32 m0, s59
	s_nop 0
	global_load_lds_dwordx4 v[220:221], off
	s_waitcnt vmcnt(8)
	s_waitcnt lgkmcnt(0)
	s_barrier
	s_waitcnt lgkmcnt(0)
	v_mfma_f32_16x16x32_bf16 v[60:63], v[144:147], v[182:185], v[60:63]
	v_mfma_f32_16x16x32_bf16 v[56:59], v[158:161], v[182:185], v[56:59]
	v_mfma_f32_16x16x32_bf16 v[44:47], v[144:147], v[190:193], v[44:47]
	v_mfma_f32_16x16x32_bf16 v[40:43], v[158:161], v[190:193], v[40:43]
	v_mfma_f32_16x16x32_bf16 v[28:31], v[144:147], v[198:201], v[28:31]
	v_mfma_f32_16x16x32_bf16 v[24:27], v[158:161], v[198:201], v[24:27]
	v_mfma_f32_16x16x32_bf16 v[12:15], v[144:147], v[206:209], v[12:15]
	v_mfma_f32_16x16x32_bf16 v[8:11], v[158:161], v[206:209], v[8:11]
	v_mfma_f32_16x16x32_bf16 v[60:63], v[154:157], v[186:189], v[60:63]
	v_mfma_f32_16x16x32_bf16 v[56:59], v[162:165], v[186:189], v[56:59]
	v_mfma_f32_16x16x32_bf16 v[44:47], v[154:157], v[194:197], v[44:47]
	v_mfma_f32_16x16x32_bf16 v[40:43], v[162:165], v[194:197], v[40:43]
	v_mfma_f32_16x16x32_bf16 v[28:31], v[154:157], v[202:205], v[28:31]
	v_mfma_f32_16x16x32_bf16 v[24:27], v[162:165], v[202:205], v[24:27]
	v_mfma_f32_16x16x32_bf16 v[12:15], v[154:157], v[210:213], v[12:15]
	v_mfma_f32_16x16x32_bf16 v[8:11], v[162:165], v[210:213], v[8:11]
	v_mfma_f32_16x16x32_bf16 v[52:55], v[166:169], v[182:185], v[52:55]
	v_mfma_f32_16x16x32_bf16 v[48:51], v[174:177], v[182:185], v[48:51]
	v_mfma_f32_16x16x32_bf16 v[36:39], v[166:169], v[190:193], v[36:39]
	v_mfma_f32_16x16x32_bf16 v[32:35], v[174:177], v[190:193], v[32:35]
	v_mfma_f32_16x16x32_bf16 v[20:23], v[166:169], v[198:201], v[20:23]
	v_mfma_f32_16x16x32_bf16 v[16:19], v[174:177], v[198:201], v[16:19]
	v_mfma_f32_16x16x32_bf16 v[4:7], v[166:169], v[206:209], v[4:7]
	v_mfma_f32_16x16x32_bf16 v[0:3], v[174:177], v[206:209], v[0:3]
	v_mfma_f32_16x16x32_bf16 v[52:55], v[170:173], v[186:189], v[52:55]
	v_mfma_f32_16x16x32_bf16 v[48:51], v[178:181], v[186:189], v[48:51]
	v_mfma_f32_16x16x32_bf16 v[36:39], v[170:173], v[194:197], v[36:39]
	v_mfma_f32_16x16x32_bf16 v[32:35], v[178:181], v[194:197], v[32:35]
	v_mfma_f32_16x16x32_bf16 v[20:23], v[170:173], v[202:205], v[20:23]
	v_mfma_f32_16x16x32_bf16 v[16:19], v[178:181], v[202:205], v[16:19]
	v_mfma_f32_16x16x32_bf16 v[4:7], v[170:173], v[210:213], v[4:7]
	v_mfma_f32_16x16x32_bf16 v[0:3], v[178:181], v[210:213], v[0:3]
	s_barrier
	s_add_i32 s44, 0, 0x18000
	s_add_i32 s45, 0, 0x1c000
	v_add_u32_e32 v162, s44, v150
	v_add_u32_e32 v178, s45, v150
	ds_read_b128 v[144:147], v162
	ds_read_b128 v[154:157], v162 offset:1024
	ds_read_b128 v[158:161], v162 offset:2048
	ds_read_b128 v[162:165], v162 offset:3072
	ds_read_b128 v[166:169], v178
	ds_read_b128 v[170:173], v178 offset:1024
	ds_read_b128 v[174:177], v178 offset:2048
	ds_read_b128 v[178:181], v178 offset:3072
	s_add_u32 s22, s50, 0xb0000
	s_addc_u32 s23, s51, 0
	s_mov_b32 m0, s60
	v_lshl_add_u64 v[222:223], s[22:23], 0, v[128:129]
	ds_read_b128 v[182:185], v153 offset:32768
	ds_read_b128 v[186:189], v153 offset:33792
	ds_read_b128 v[190:193], v153 offset:34816
	ds_read_b128 v[194:197], v153 offset:35840
	ds_read_b128 v[198:201], v153 offset:36864
	ds_read_b128 v[202:205], v153 offset:37888
	ds_read_b128 v[206:209], v153 offset:38912
	ds_read_b128 v[210:213], v153 offset:39936
	global_load_lds_dwordx4 v[222:223], off
	v_lshl_add_u64 v[222:223], s[22:23], 0, v[132:133]
	s_mov_b32 m0, s61
	s_nop 0
	global_load_lds_dwordx4 v[222:223], off
	s_waitcnt vmcnt(8)
	s_waitcnt lgkmcnt(0)
	s_barrier
	s_waitcnt lgkmcnt(0)
	v_mfma_f32_16x16x32_bf16 v[124:127], v[144:147], v[182:185], v[124:127]
	v_mfma_f32_16x16x32_bf16 v[120:123], v[158:161], v[182:185], v[120:123]
	v_mfma_f32_16x16x32_bf16 v[108:111], v[144:147], v[190:193], v[108:111]
	v_mfma_f32_16x16x32_bf16 v[104:107], v[158:161], v[190:193], v[104:107]
	v_mfma_f32_16x16x32_bf16 v[92:95], v[144:147], v[198:201], v[92:95]
	v_mfma_f32_16x16x32_bf16 v[88:91], v[158:161], v[198:201], v[88:91]
	v_mfma_f32_16x16x32_bf16 v[76:79], v[144:147], v[206:209], v[76:79]
	v_mfma_f32_16x16x32_bf16 v[72:75], v[158:161], v[206:209], v[72:75]
	v_mfma_f32_16x16x32_bf16 v[124:127], v[154:157], v[186:189], v[124:127]
	v_mfma_f32_16x16x32_bf16 v[120:123], v[162:165], v[186:189], v[120:123]
	v_mfma_f32_16x16x32_bf16 v[108:111], v[154:157], v[194:197], v[108:111]
	v_mfma_f32_16x16x32_bf16 v[104:107], v[162:165], v[194:197], v[104:107]
	v_mfma_f32_16x16x32_bf16 v[92:95], v[154:157], v[202:205], v[92:95]
	v_mfma_f32_16x16x32_bf16 v[88:91], v[162:165], v[202:205], v[88:91]
	v_mfma_f32_16x16x32_bf16 v[76:79], v[154:157], v[210:213], v[76:79]
	v_mfma_f32_16x16x32_bf16 v[72:75], v[162:165], v[210:213], v[72:75]
	v_mfma_f32_16x16x32_bf16 v[116:119], v[166:169], v[182:185], v[116:119]
	v_mfma_f32_16x16x32_bf16 v[112:115], v[174:177], v[182:185], v[112:115]
	v_mfma_f32_16x16x32_bf16 v[100:103], v[166:169], v[190:193], v[100:103]
	v_mfma_f32_16x16x32_bf16 v[96:99], v[174:177], v[190:193], v[96:99]
	v_mfma_f32_16x16x32_bf16 v[84:87], v[166:169], v[198:201], v[84:87]
	v_mfma_f32_16x16x32_bf16 v[80:83], v[174:177], v[198:201], v[80:83]
	v_mfma_f32_16x16x32_bf16 v[68:71], v[166:169], v[206:209], v[68:71]
	v_mfma_f32_16x16x32_bf16 v[64:67], v[174:177], v[206:209], v[64:67]
	v_mfma_f32_16x16x32_bf16 v[116:119], v[170:173], v[186:189], v[116:119]
	v_mfma_f32_16x16x32_bf16 v[112:115], v[178:181], v[186:189], v[112:115]
	v_mfma_f32_16x16x32_bf16 v[100:103], v[170:173], v[194:197], v[100:103]
	v_mfma_f32_16x16x32_bf16 v[96:99], v[178:181], v[194:197], v[96:99]
	v_mfma_f32_16x16x32_bf16 v[84:87], v[170:173], v[202:205], v[84:87]
	v_mfma_f32_16x16x32_bf16 v[80:83], v[178:181], v[202:205], v[80:83]
	v_mfma_f32_16x16x32_bf16 v[68:71], v[170:173], v[210:213], v[68:71]
	v_mfma_f32_16x16x32_bf16 v[64:67], v[178:181], v[210:213], v[64:67]
	s_barrier
	s_add_i32 s22, s44, s57
	v_lshl_add_u64 v[214:215], v[214:215], 0, s[38:39]
	s_mov_b32 m0, s22
	ds_read_b128 v[182:185], v153 offset:49152
	ds_read_b128 v[186:189], v153 offset:50176
	ds_read_b128 v[190:193], v153 offset:51200
	ds_read_b128 v[194:197], v153 offset:52224
	ds_read_b128 v[198:201], v153 offset:53248
	ds_read_b128 v[202:205], v153 offset:54272
	ds_read_b128 v[206:209], v153 offset:55296
	ds_read_b128 v[210:213], v153 offset:56320
	global_load_lds_dwordx4 v[214:215], off
	s_add_i32 m0, s22, 0x2000
	s_add_u32 s22, s48, 0xb0080
	v_lshl_add_u64 v[214:215], v[216:217], 0, s[38:39]
	s_addc_u32 s23, s49, 0
	s_add_i32 s44, s45, s57
	global_load_lds_dwordx4 v[214:215], off
	v_lshl_add_u64 v[214:215], s[22:23], 0, v[130:131]
	s_mov_b32 m0, s44
	s_nop 0
	global_load_lds_dwordx4 v[214:215], off
	v_lshl_add_u64 v[214:215], s[22:23], 0, v[134:135]
	s_add_i32 m0, s44, 0x2000
	s_nop 0
	global_load_lds_dwordx4 v[214:215], off
	v_lshl_add_u64 v[214:215], v[218:219], 0, s[38:39]
	s_mov_b32 m0, s65
	s_nop 0
	global_load_lds_dwordx4 v[214:215], off
	v_lshl_add_u64 v[214:215], v[220:221], 0, s[38:39]
	s_mov_b32 m0, s66
	s_nop 0
	global_load_lds_dwordx4 v[214:215], off
	s_waitcnt vmcnt(8)
	s_waitcnt lgkmcnt(0)
	s_barrier
	s_waitcnt lgkmcnt(0)
	v_mfma_f32_16x16x32_bf16 v[60:63], v[144:147], v[182:185], v[60:63]
	v_mfma_f32_16x16x32_bf16 v[56:59], v[158:161], v[182:185], v[56:59]
	v_mfma_f32_16x16x32_bf16 v[44:47], v[144:147], v[190:193], v[44:47]
	v_mfma_f32_16x16x32_bf16 v[40:43], v[158:161], v[190:193], v[40:43]
	v_mfma_f32_16x16x32_bf16 v[28:31], v[144:147], v[198:201], v[28:31]
	v_mfma_f32_16x16x32_bf16 v[24:27], v[158:161], v[198:201], v[24:27]
	v_mfma_f32_16x16x32_bf16 v[12:15], v[144:147], v[206:209], v[12:15]
	v_mfma_f32_16x16x32_bf16 v[8:11], v[158:161], v[206:209], v[8:11]
	v_mfma_f32_16x16x32_bf16 v[60:63], v[154:157], v[186:189], v[60:63]
	v_mfma_f32_16x16x32_bf16 v[56:59], v[162:165], v[186:189], v[56:59]
	v_mfma_f32_16x16x32_bf16 v[44:47], v[154:157], v[194:197], v[44:47]
	v_mfma_f32_16x16x32_bf16 v[40:43], v[162:165], v[194:197], v[40:43]
	v_mfma_f32_16x16x32_bf16 v[28:31], v[154:157], v[202:205], v[28:31]
	v_mfma_f32_16x16x32_bf16 v[24:27], v[162:165], v[202:205], v[24:27]
	v_mfma_f32_16x16x32_bf16 v[12:15], v[154:157], v[210:213], v[12:15]
	v_mfma_f32_16x16x32_bf16 v[8:11], v[162:165], v[210:213], v[8:11]
	v_mfma_f32_16x16x32_bf16 v[52:55], v[166:169], v[182:185], v[52:55]
	v_mfma_f32_16x16x32_bf16 v[48:51], v[174:177], v[182:185], v[48:51]
	v_mfma_f32_16x16x32_bf16 v[36:39], v[166:169], v[190:193], v[36:39]
	v_mfma_f32_16x16x32_bf16 v[32:35], v[174:177], v[190:193], v[32:35]
	v_mfma_f32_16x16x32_bf16 v[20:23], v[166:169], v[198:201], v[20:23]
	v_mfma_f32_16x16x32_bf16 v[16:19], v[174:177], v[198:201], v[16:19]
	v_mfma_f32_16x16x32_bf16 v[4:7], v[166:169], v[206:209], v[4:7]
	v_mfma_f32_16x16x32_bf16 v[0:3], v[174:177], v[206:209], v[0:3]
	v_mfma_f32_16x16x32_bf16 v[52:55], v[170:173], v[186:189], v[52:55]
	v_mfma_f32_16x16x32_bf16 v[48:51], v[178:181], v[186:189], v[48:51]
	v_mfma_f32_16x16x32_bf16 v[36:39], v[170:173], v[194:197], v[36:39]
	v_mfma_f32_16x16x32_bf16 v[32:35], v[178:181], v[194:197], v[32:35]
	v_mfma_f32_16x16x32_bf16 v[20:23], v[170:173], v[202:205], v[20:23]
	v_mfma_f32_16x16x32_bf16 v[16:19], v[178:181], v[202:205], v[16:19]
	v_mfma_f32_16x16x32_bf16 v[4:7], v[170:173], v[210:213], v[4:7]
	v_mfma_f32_16x16x32_bf16 v[0:3], v[178:181], v[210:213], v[0:3]
	s_barrier
	s_add_i32 s71, s71, 2
	s_add_u32 s26, s26, 0x100
	s_addc_u32 s27, s27, 0
	s_cmp_gt_u32 s71, 41
	s_mov_b64 s[44:45], s[46:47]
	s_cbranch_scc0 .LBB0_1059
	s_and_b64 vcc, exec, s[40:41]
	s_cbranch_vccz .LBB0_1062
	s_barrier

.LBB0_1161:
	ds_read_b128 v[144:147], v155
	ds_read_b128 v[148:151], v155 offset:1024
	ds_read_b128 v[158:161], v155 offset:2048
	ds_read_b128 v[162:165], v155 offset:3072
	ds_read_b128 v[166:169], v156
	ds_read_b128 v[170:173], v156 offset:1024
	ds_read_b128 v[174:177], v156 offset:2048
	ds_read_b128 v[178:181], v156 offset:3072
	s_add_u32 s22, s58, 0xfffc0080
	s_addc_u32 s23, s59, -1
	s_cmp_eq_u32 s94, 12
	s_cselect_b32 s63, s13, s23
	s_cselect_b32 s62, s26, s22
	s_cselect_b32 s61, s27, s57
	s_cselect_b32 s60, s49, s51
	v_lshl_add_u64 v[214:215], s[58:59], 0, v[138:139]
	s_add_i32 m0, s71, 0xc000
	ds_read_b128 v[182:185], v157
	ds_read_b128 v[186:189], v157 offset:1024
	ds_read_b128 v[190:193], v157 offset:2048
	ds_read_b128 v[194:197], v157 offset:3072
	ds_read_b128 v[198:201], v157 offset:4096
	ds_read_b128 v[202:205], v157 offset:5120
	ds_read_b128 v[206:209], v157 offset:6144
	ds_read_b128 v[210:213], v157 offset:7168
	global_load_lds_dwordx4 v[214:215], off
	v_lshl_add_u64 v[214:215], s[58:59], 0, v[136:137]
	s_add_i32 m0, s71, 0xe000
	s_nop 0
	global_load_lds_dwordx4 v[214:215], off
	s_waitcnt vmcnt(8)
	s_waitcnt lgkmcnt(0)
	s_barrier
	s_waitcnt lgkmcnt(0)
	v_mfma_f32_16x16x32_bf16 v[124:127], v[144:147], v[182:185], v[124:127]
	v_mfma_f32_16x16x32_bf16 v[120:123], v[158:161], v[182:185], v[120:123]
	v_mfma_f32_16x16x32_bf16 v[108:111], v[144:147], v[190:193], v[108:111]
	v_mfma_f32_16x16x32_bf16 v[104:107], v[158:161], v[190:193], v[104:107]
	v_mfma_f32_16x16x32_bf16 v[92:95], v[144:147], v[198:201], v[92:95]
	v_mfma_f32_16x16x32_bf16 v[88:91], v[158:161], v[198:201], v[88:91]
	v_mfma_f32_16x16x32_bf16 v[76:79], v[144:147], v[206:209], v[76:79]
	v_mfma_f32_16x16x32_bf16 v[72:75], v[158:161], v[206:209], v[72:75]
	v_mfma_f32_16x16x32_bf16 v[124:127], v[148:151], v[186:189], v[124:127]
	v_mfma_f32_16x16x32_bf16 v[120:123], v[162:165], v[186:189], v[120:123]
	v_mfma_f32_16x16x32_bf16 v[108:111], v[148:151], v[194:197], v[108:111]
	v_mfma_f32_16x16x32_bf16 v[104:107], v[162:165], v[194:197], v[104:107]
	v_mfma_f32_16x16x32_bf16 v[92:95], v[148:151], v[202:205], v[92:95]
	v_mfma_f32_16x16x32_bf16 v[88:91], v[162:165], v[202:205], v[88:91]
	v_mfma_f32_16x16x32_bf16 v[76:79], v[148:151], v[210:213], v[76:79]
	v_mfma_f32_16x16x32_bf16 v[72:75], v[162:165], v[210:213], v[72:75]
	v_mfma_f32_16x16x32_bf16 v[116:119], v[166:169], v[182:185], v[116:119]
	v_mfma_f32_16x16x32_bf16 v[112:115], v[174:177], v[182:185], v[112:115]
	v_mfma_f32_16x16x32_bf16 v[100:103], v[166:169], v[190:193], v[100:103]
	v_mfma_f32_16x16x32_bf16 v[96:99], v[174:177], v[190:193], v[96:99]
	v_mfma_f32_16x16x32_bf16 v[84:87], v[166:169], v[198:201], v[84:87]
	v_mfma_f32_16x16x32_bf16 v[80:83], v[174:177], v[198:201], v[80:83]
	v_mfma_f32_16x16x32_bf16 v[68:71], v[166:169], v[206:209], v[68:71]
	v_mfma_f32_16x16x32_bf16 v[64:67], v[174:177], v[206:209], v[64:67]
	v_mfma_f32_16x16x32_bf16 v[116:119], v[170:173], v[186:189], v[116:119]
	v_mfma_f32_16x16x32_bf16 v[112:115], v[178:181], v[186:189], v[112:115]
	v_mfma_f32_16x16x32_bf16 v[100:103], v[170:173], v[194:197], v[100:103]
	v_mfma_f32_16x16x32_bf16 v[96:99], v[178:181], v[194:197], v[96:99]
	v_mfma_f32_16x16x32_bf16 v[84:87], v[170:173], v[202:205], v[84:87]
	v_mfma_f32_16x16x32_bf16 v[80:83], v[178:181], v[202:205], v[80:83]
	v_mfma_f32_16x16x32_bf16 v[68:71], v[170:173], v[210:213], v[68:71]
	v_mfma_f32_16x16x32_bf16 v[64:67], v[178:181], v[210:213], v[64:67]
	s_barrier
	s_add_i32 s22, s91, s65
	v_lshl_add_u64 v[214:215], s[60:61], 0, v[130:131]
	s_mov_b32 m0, s22
	ds_read_b128 v[182:185], v157 offset:16384
	ds_read_b128 v[186:189], v157 offset:17408
	ds_read_b128 v[190:193], v157 offset:18432
	ds_read_b128 v[194:197], v157 offset:19456
	ds_read_b128 v[198:201], v157 offset:20480
	ds_read_b128 v[202:205], v157 offset:21504
	ds_read_b128 v[206:209], v157 offset:22528
	ds_read_b128 v[210:213], v157 offset:23552
	global_load_lds_dwordx4 v[214:215], off
	s_add_i32 m0, s22, 0x2000
	s_add_u32 s22, s60, 0x40000
	v_lshl_add_u64 v[216:217], s[60:61], 0, v[134:135]
	s_addc_u32 s23, s61, 0
	s_add_i32 s70, s92, s65
	global_load_lds_dwordx4 v[216:217], off
	v_lshl_add_u64 v[218:219], s[22:23], 0, v[130:131]
	s_mov_b32 m0, s70
	v_lshl_add_u64 v[220:221], s[62:63], 0, v[132:133]
	global_load_lds_dwordx4 v[218:219], off
	v_lshl_add_u64 v[218:219], s[22:23], 0, v[134:135]
	s_add_i32 m0, s70, 0x2000
	s_nop 0
	global_load_lds_dwordx4 v[218:219], off
	v_lshl_add_u64 v[218:219], s[62:63], 0, v[128:129]
	s_mov_b32 m0, s71
	s_nop 0
	global_load_lds_dwordx4 v[218:219], off
	s_mov_b32 m0, s82
	s_nop 0
	global_load_lds_dwordx4 v[220:221], off
	s_waitcnt vmcnt(8)
	s_waitcnt lgkmcnt(0)
	s_barrier
	s_waitcnt lgkmcnt(0)
	v_mfma_f32_16x16x32_bf16 v[60:63], v[144:147], v[182:185], v[60:63]
	v_mfma_f32_16x16x32_bf16 v[56:59], v[158:161], v[182:185], v[56:59]
	v_mfma_f32_16x16x32_bf16 v[44:47], v[144:147], v[190:193], v[44:47]
	v_mfma_f32_16x16x32_bf16 v[40:43], v[158:161], v[190:193], v[40:43]
	v_mfma_f32_16x16x32_bf16 v[28:31], v[144:147], v[198:201], v[28:31]
	v_mfma_f32_16x16x32_bf16 v[24:27], v[158:161], v[198:201], v[24:27]
	v_mfma_f32_16x16x32_bf16 v[12:15], v[144:147], v[206:209], v[12:15]
	v_mfma_f32_16x16x32_bf16 v[8:11], v[158:161], v[206:209], v[8:11]
	v_mfma_f32_16x16x32_bf16 v[60:63], v[148:151], v[186:189], v[60:63]
	v_mfma_f32_16x16x32_bf16 v[56:59], v[162:165], v[186:189], v[56:59]
	v_mfma_f32_16x16x32_bf16 v[44:47], v[148:151], v[194:197], v[44:47]
	v_mfma_f32_16x16x32_bf16 v[40:43], v[162:165], v[194:197], v[40:43]
	v_mfma_f32_16x16x32_bf16 v[28:31], v[148:151], v[202:205], v[28:31]
	v_mfma_f32_16x16x32_bf16 v[24:27], v[162:165], v[202:205], v[24:27]
	v_mfma_f32_16x16x32_bf16 v[12:15], v[148:151], v[210:213], v[12:15]
	v_mfma_f32_16x16x32_bf16 v[8:11], v[162:165], v[210:213], v[8:11]
	v_mfma_f32_16x16x32_bf16 v[52:55], v[166:169], v[182:185], v[52:55]
	v_mfma_f32_16x16x32_bf16 v[48:51], v[174:177], v[182:185], v[48:51]
	v_mfma_f32_16x16x32_bf16 v[36:39], v[166:169], v[190:193], v[36:39]
	v_mfma_f32_16x16x32_bf16 v[32:35], v[174:177], v[190:193], v[32:35]
	v_mfma_f32_16x16x32_bf16 v[20:23], v[166:169], v[198:201], v[20:23]
	v_mfma_f32_16x16x32_bf16 v[16:19], v[174:177], v[198:201], v[16:19]
	v_mfma_f32_16x16x32_bf16 v[4:7], v[166:169], v[206:209], v[4:7]
	v_mfma_f32_16x16x32_bf16 v[0:3], v[174:177], v[206:209], v[0:3]
	v_mfma_f32_16x16x32_bf16 v[52:55], v[170:173], v[186:189], v[52:55]
	v_mfma_f32_16x16x32_bf16 v[48:51], v[178:181], v[186:189], v[48:51]
	v_mfma_f32_16x16x32_bf16 v[36:39], v[170:173], v[194:197], v[36:39]
	v_mfma_f32_16x16x32_bf16 v[32:35], v[178:181], v[194:197], v[32:35]
	v_mfma_f32_16x16x32_bf16 v[20:23], v[170:173], v[202:205], v[20:23]
	v_mfma_f32_16x16x32_bf16 v[16:19], v[178:181], v[202:205], v[16:19]
	v_mfma_f32_16x16x32_bf16 v[4:7], v[170:173], v[210:213], v[4:7]
	v_mfma_f32_16x16x32_bf16 v[0:3], v[178:181], v[210:213], v[0:3]
	s_barrier
	s_add_i32 s70, 0, 0x18000
	s_add_i32 s81, 0, 0x1c000
	v_add_u32_e32 v162, s70, v154
	v_add_u32_e32 v178, s81, v154
	ds_read_b128 v[144:147], v162
	ds_read_b128 v[148:151], v162 offset:1024
	ds_read_b128 v[158:161], v162 offset:2048
	ds_read_b128 v[162:165], v162 offset:3072
	ds_read_b128 v[166:169], v178
	ds_read_b128 v[170:173], v178 offset:1024
	ds_read_b128 v[174:177], v178 offset:2048
	ds_read_b128 v[178:181], v178 offset:3072
	s_add_u32 s22, s62, 0x40000
	s_addc_u32 s23, s63, 0
	s_mov_b32 m0, s83
	v_lshl_add_u64 v[222:223], s[22:23], 0, v[128:129]
	ds_read_b128 v[182:185], v157 offset:32768
	ds_read_b128 v[186:189], v157 offset:33792
	ds_read_b128 v[190:193], v157 offset:34816
	ds_read_b128 v[194:197], v157 offset:35840
	ds_read_b128 v[198:201], v157 offset:36864
	ds_read_b128 v[202:205], v157 offset:37888
	ds_read_b128 v[206:209], v157 offset:38912
	ds_read_b128 v[210:213], v157 offset:39936
	global_load_lds_dwordx4 v[222:223], off
	v_lshl_add_u64 v[222:223], s[22:23], 0, v[132:133]
	s_mov_b32 m0, s84
	s_nop 0
	global_load_lds_dwordx4 v[222:223], off
	s_waitcnt vmcnt(8)
	s_waitcnt lgkmcnt(0)
	s_barrier
	s_waitcnt lgkmcnt(0)
	v_mfma_f32_16x16x32_bf16 v[124:127], v[144:147], v[182:185], v[124:127]
	v_mfma_f32_16x16x32_bf16 v[120:123], v[158:161], v[182:185], v[120:123]
	v_mfma_f32_16x16x32_bf16 v[108:111], v[144:147], v[190:193], v[108:111]
	v_mfma_f32_16x16x32_bf16 v[104:107], v[158:161], v[190:193], v[104:107]
	v_mfma_f32_16x16x32_bf16 v[92:95], v[144:147], v[198:201], v[92:95]
	v_mfma_f32_16x16x32_bf16 v[88:91], v[158:161], v[198:201], v[88:91]
	v_mfma_f32_16x16x32_bf16 v[76:79], v[144:147], v[206:209], v[76:79]
	v_mfma_f32_16x16x32_bf16 v[72:75], v[158:161], v[206:209], v[72:75]
	v_mfma_f32_16x16x32_bf16 v[124:127], v[148:151], v[186:189], v[124:127]
	v_mfma_f32_16x16x32_bf16 v[120:123], v[162:165], v[186:189], v[120:123]
	v_mfma_f32_16x16x32_bf16 v[108:111], v[148:151], v[194:197], v[108:111]
	v_mfma_f32_16x16x32_bf16 v[104:107], v[162:165], v[194:197], v[104:107]
	v_mfma_f32_16x16x32_bf16 v[92:95], v[148:151], v[202:205], v[92:95]
	v_mfma_f32_16x16x32_bf16 v[88:91], v[162:165], v[202:205], v[88:91]
	v_mfma_f32_16x16x32_bf16 v[76:79], v[148:151], v[210:213], v[76:79]
	v_mfma_f32_16x16x32_bf16 v[72:75], v[162:165], v[210:213], v[72:75]
	v_mfma_f32_16x16x32_bf16 v[116:119], v[166:169], v[182:185], v[116:119]
	v_mfma_f32_16x16x32_bf16 v[112:115], v[174:177], v[182:185], v[112:115]
	v_mfma_f32_16x16x32_bf16 v[100:103], v[166:169], v[190:193], v[100:103]
	v_mfma_f32_16x16x32_bf16 v[96:99], v[174:177], v[190:193], v[96:99]
	v_mfma_f32_16x16x32_bf16 v[84:87], v[166:169], v[198:201], v[84:87]
	v_mfma_f32_16x16x32_bf16 v[80:83], v[174:177], v[198:201], v[80:83]
	v_mfma_f32_16x16x32_bf16 v[68:71], v[166:169], v[206:209], v[68:71]
	v_mfma_f32_16x16x32_bf16 v[64:67], v[174:177], v[206:209], v[64:67]
	v_mfma_f32_16x16x32_bf16 v[116:119], v[170:173], v[186:189], v[116:119]
	v_mfma_f32_16x16x32_bf16 v[112:115], v[178:181], v[186:189], v[112:115]
	v_mfma_f32_16x16x32_bf16 v[100:103], v[170:173], v[194:197], v[100:103]
	v_mfma_f32_16x16x32_bf16 v[96:99], v[178:181], v[194:197], v[96:99]
	v_mfma_f32_16x16x32_bf16 v[84:87], v[170:173], v[202:205], v[84:87]
	v_mfma_f32_16x16x32_bf16 v[80:83], v[178:181], v[202:205], v[80:83]
	v_mfma_f32_16x16x32_bf16 v[68:71], v[170:173], v[210:213], v[68:71]
	v_mfma_f32_16x16x32_bf16 v[64:67], v[178:181], v[210:213], v[64:67]
	s_barrier
	s_add_i32 s22, s70, s65
	v_lshl_add_u64 v[214:215], v[214:215], 0, s[44:45]
	s_mov_b32 m0, s22
	ds_read_b128 v[182:185], v157 offset:49152
	ds_read_b128 v[186:189], v157 offset:50176
	ds_read_b128 v[190:193], v157 offset:51200
	ds_read_b128 v[194:197], v157 offset:52224
	ds_read_b128 v[198:201], v157 offset:53248
	ds_read_b128 v[202:205], v157 offset:54272
	ds_read_b128 v[206:209], v157 offset:55296
	ds_read_b128 v[210:213], v157 offset:56320
	global_load_lds_dwordx4 v[214:215], off
	s_add_i32 m0, s22, 0x2000
	s_add_u32 s22, s60, 0x40080
	v_lshl_add_u64 v[214:215], v[216:217], 0, s[44:45]
	s_addc_u32 s23, s61, 0
	s_add_i32 s60, s81, s65
	global_load_lds_dwordx4 v[214:215], off
	v_lshl_add_u64 v[214:215], s[22:23], 0, v[130:131]
	s_mov_b32 m0, s60
	s_nop 0
	global_load_lds_dwordx4 v[214:215], off
	v_lshl_add_u64 v[214:215], s[22:23], 0, v[134:135]
	s_add_i32 m0, s60, 0x2000
	s_nop 0
	global_load_lds_dwordx4 v[214:215], off
	v_lshl_add_u64 v[214:215], v[218:219], 0, s[44:45]
	s_mov_b32 m0, s88
	s_nop 0
	global_load_lds_dwordx4 v[214:215], off
	v_lshl_add_u64 v[214:215], v[220:221], 0, s[44:45]
	s_mov_b32 m0, s89
	s_nop 0
	global_load_lds_dwordx4 v[214:215], off
	s_waitcnt vmcnt(8)
	s_waitcnt lgkmcnt(0)
	s_barrier
	s_waitcnt lgkmcnt(0)
	v_mfma_f32_16x16x32_bf16 v[60:63], v[144:147], v[182:185], v[60:63]
	v_mfma_f32_16x16x32_bf16 v[56:59], v[158:161], v[182:185], v[56:59]
	v_mfma_f32_16x16x32_bf16 v[44:47], v[144:147], v[190:193], v[44:47]
	v_mfma_f32_16x16x32_bf16 v[40:43], v[158:161], v[190:193], v[40:43]
	v_mfma_f32_16x16x32_bf16 v[28:31], v[144:147], v[198:201], v[28:31]
	v_mfma_f32_16x16x32_bf16 v[24:27], v[158:161], v[198:201], v[24:27]
	v_mfma_f32_16x16x32_bf16 v[12:15], v[144:147], v[206:209], v[12:15]
	v_mfma_f32_16x16x32_bf16 v[8:11], v[158:161], v[206:209], v[8:11]
	v_mfma_f32_16x16x32_bf16 v[60:63], v[148:151], v[186:189], v[60:63]
	v_mfma_f32_16x16x32_bf16 v[56:59], v[162:165], v[186:189], v[56:59]
	v_mfma_f32_16x16x32_bf16 v[44:47], v[148:151], v[194:197], v[44:47]
	v_mfma_f32_16x16x32_bf16 v[40:43], v[162:165], v[194:197], v[40:43]
	v_mfma_f32_16x16x32_bf16 v[28:31], v[148:151], v[202:205], v[28:31]
	v_mfma_f32_16x16x32_bf16 v[24:27], v[162:165], v[202:205], v[24:27]
	v_mfma_f32_16x16x32_bf16 v[12:15], v[148:151], v[210:213], v[12:15]
	v_mfma_f32_16x16x32_bf16 v[8:11], v[162:165], v[210:213], v[8:11]
	v_mfma_f32_16x16x32_bf16 v[52:55], v[166:169], v[182:185], v[52:55]
	v_mfma_f32_16x16x32_bf16 v[48:51], v[174:177], v[182:185], v[48:51]
	v_mfma_f32_16x16x32_bf16 v[36:39], v[166:169], v[190:193], v[36:39]
	v_mfma_f32_16x16x32_bf16 v[32:35], v[174:177], v[190:193], v[32:35]
	v_mfma_f32_16x16x32_bf16 v[20:23], v[166:169], v[198:201], v[20:23]
	v_mfma_f32_16x16x32_bf16 v[16:19], v[174:177], v[198:201], v[16:19]
	v_mfma_f32_16x16x32_bf16 v[4:7], v[166:169], v[206:209], v[4:7]
	v_mfma_f32_16x16x32_bf16 v[0:3], v[174:177], v[206:209], v[0:3]
	v_mfma_f32_16x16x32_bf16 v[52:55], v[170:173], v[186:189], v[52:55]
	v_mfma_f32_16x16x32_bf16 v[48:51], v[178:181], v[186:189], v[48:51]
	v_mfma_f32_16x16x32_bf16 v[36:39], v[170:173], v[194:197], v[36:39]
	v_mfma_f32_16x16x32_bf16 v[32:35], v[178:181], v[194:197], v[32:35]
	v_mfma_f32_16x16x32_bf16 v[20:23], v[170:173], v[202:205], v[20:23]
	v_mfma_f32_16x16x32_bf16 v[16:19], v[178:181], v[202:205], v[16:19]
	v_mfma_f32_16x16x32_bf16 v[4:7], v[170:173], v[210:213], v[4:7]
	v_mfma_f32_16x16x32_bf16 v[0:3], v[178:181], v[210:213], v[0:3]
	s_barrier
	s_add_i32 s94, s94, 2
	s_add_u32 s51, s51, 0x100
	s_addc_u32 s57, s57, 0
	s_add_u32 s58, s58, 0x100
	s_addc_u32 s59, s59, 0
	s_cmp_gt_u32 s94, 13
	s_cbranch_scc0 .LBB0_1161
	s_and_b64 vcc, exec, s[46:47]
	s_cbranch_vccz .LBB0_1164
	s_barrier

.LBB0_1603:
	ds_read_b128 v[144:147], v151
	ds_read_b128 v[154:157], v151 offset:1024
	ds_read_b128 v[158:161], v151 offset:2048
	ds_read_b128 v[162:165], v151 offset:3072
	ds_read_b128 v[166:169], v152
	ds_read_b128 v[170:173], v152 offset:1024
	ds_read_b128 v[174:177], v152 offset:2048
	ds_read_b128 v[178:181], v152 offset:3072
	s_add_u32 s48, s46, 0xfffc0080
	s_addc_u32 s49, s47, -1
	s_cmp_eq_u32 s71, 12
	s_cselect_b32 s51, s26, s49
	s_cselect_b32 s50, s27, s48
	s_cselect_b32 s49, s39, s69
	s_cselect_b32 s48, s41, s68
	v_lshl_add_u64 v[214:215], s[46:47], 0, v[138:139]
	s_add_i32 m0, s15, 0xc000
	ds_read_b128 v[182:185], v153
	ds_read_b128 v[186:189], v153 offset:1024
	ds_read_b128 v[190:193], v153 offset:2048
	ds_read_b128 v[194:197], v153 offset:3072
	ds_read_b128 v[198:201], v153 offset:4096
	ds_read_b128 v[202:205], v153 offset:5120
	ds_read_b128 v[206:209], v153 offset:6144
	ds_read_b128 v[210:213], v153 offset:7168
	global_load_lds_dwordx4 v[214:215], off
	v_lshl_add_u64 v[214:215], s[46:47], 0, v[136:137]
	s_add_i32 m0, s15, 0xe000
	s_nop 0
	global_load_lds_dwordx4 v[214:215], off
	s_waitcnt vmcnt(8)
	s_waitcnt lgkmcnt(0)
	s_barrier
	s_waitcnt lgkmcnt(0)
	v_mfma_f32_16x16x32_bf16 v[124:127], v[144:147], v[182:185], v[124:127]
	v_mfma_f32_16x16x32_bf16 v[120:123], v[158:161], v[182:185], v[120:123]
	v_mfma_f32_16x16x32_bf16 v[108:111], v[144:147], v[190:193], v[108:111]
	v_mfma_f32_16x16x32_bf16 v[104:107], v[158:161], v[190:193], v[104:107]
	v_mfma_f32_16x16x32_bf16 v[92:95], v[144:147], v[198:201], v[92:95]
	v_mfma_f32_16x16x32_bf16 v[88:91], v[158:161], v[198:201], v[88:91]
	v_mfma_f32_16x16x32_bf16 v[76:79], v[144:147], v[206:209], v[76:79]
	v_mfma_f32_16x16x32_bf16 v[72:75], v[158:161], v[206:209], v[72:75]
	v_mfma_f32_16x16x32_bf16 v[124:127], v[154:157], v[186:189], v[124:127]
	v_mfma_f32_16x16x32_bf16 v[120:123], v[162:165], v[186:189], v[120:123]
	v_mfma_f32_16x16x32_bf16 v[108:111], v[154:157], v[194:197], v[108:111]
	v_mfma_f32_16x16x32_bf16 v[104:107], v[162:165], v[194:197], v[104:107]
	v_mfma_f32_16x16x32_bf16 v[92:95], v[154:157], v[202:205], v[92:95]
	v_mfma_f32_16x16x32_bf16 v[88:91], v[162:165], v[202:205], v[88:91]
	v_mfma_f32_16x16x32_bf16 v[76:79], v[154:157], v[210:213], v[76:79]
	v_mfma_f32_16x16x32_bf16 v[72:75], v[162:165], v[210:213], v[72:75]
	v_mfma_f32_16x16x32_bf16 v[116:119], v[166:169], v[182:185], v[116:119]
	v_mfma_f32_16x16x32_bf16 v[112:115], v[174:177], v[182:185], v[112:115]
	v_mfma_f32_16x16x32_bf16 v[100:103], v[166:169], v[190:193], v[100:103]
	v_mfma_f32_16x16x32_bf16 v[96:99], v[174:177], v[190:193], v[96:99]
	v_mfma_f32_16x16x32_bf16 v[84:87], v[166:169], v[198:201], v[84:87]
	v_mfma_f32_16x16x32_bf16 v[80:83], v[174:177], v[198:201], v[80:83]
	v_mfma_f32_16x16x32_bf16 v[68:71], v[166:169], v[206:209], v[68:71]
	v_mfma_f32_16x16x32_bf16 v[64:67], v[174:177], v[206:209], v[64:67]
	v_mfma_f32_16x16x32_bf16 v[116:119], v[170:173], v[186:189], v[116:119]
	v_mfma_f32_16x16x32_bf16 v[112:115], v[178:181], v[186:189], v[112:115]
	v_mfma_f32_16x16x32_bf16 v[100:103], v[170:173], v[194:197], v[100:103]
	v_mfma_f32_16x16x32_bf16 v[96:99], v[178:181], v[194:197], v[96:99]
	v_mfma_f32_16x16x32_bf16 v[84:87], v[170:173], v[202:205], v[84:87]
	v_mfma_f32_16x16x32_bf16 v[80:83], v[178:181], v[202:205], v[80:83]
	v_mfma_f32_16x16x32_bf16 v[68:71], v[170:173], v[210:213], v[68:71]
	v_mfma_f32_16x16x32_bf16 v[64:67], v[178:181], v[210:213], v[64:67]
	s_barrier
	s_add_i32 s70, s65, s56
	v_lshl_add_u64 v[214:215], s[48:49], 0, v[130:131]
	s_mov_b32 m0, s70
	ds_read_b128 v[182:185], v153 offset:16384
	ds_read_b128 v[186:189], v153 offset:17408
	ds_read_b128 v[190:193], v153 offset:18432
	ds_read_b128 v[194:197], v153 offset:19456
	ds_read_b128 v[198:201], v153 offset:20480
	ds_read_b128 v[202:205], v153 offset:21504
	ds_read_b128 v[206:209], v153 offset:22528
	ds_read_b128 v[210:213], v153 offset:23552
	global_load_lds_dwordx4 v[214:215], off
	s_add_i32 m0, s70, 0x2000
	s_add_u32 s78, s48, 0x40000
	v_lshl_add_u64 v[216:217], s[48:49], 0, v[134:135]
	s_addc_u32 s79, s49, 0
	s_add_i32 s70, s66, s56
	global_load_lds_dwordx4 v[216:217], off
	v_lshl_add_u64 v[218:219], s[78:79], 0, v[130:131]
	s_mov_b32 m0, s70
	v_lshl_add_u64 v[220:221], s[50:51], 0, v[132:133]
	global_load_lds_dwordx4 v[218:219], off
	v_lshl_add_u64 v[218:219], s[78:79], 0, v[134:135]
	s_add_i32 m0, s70, 0x2000
	s_nop 0
	global_load_lds_dwordx4 v[218:219], off
	v_lshl_add_u64 v[218:219], s[50:51], 0, v[128:129]
	s_mov_b32 m0, s15
	s_nop 0
	global_load_lds_dwordx4 v[218:219], off
	s_mov_b32 m0, s57
	s_nop 0
	global_load_lds_dwordx4 v[220:221], off
	s_waitcnt vmcnt(8)
	s_waitcnt lgkmcnt(0)
	s_barrier
	s_waitcnt lgkmcnt(0)
	v_mfma_f32_16x16x32_bf16 v[60:63], v[144:147], v[182:185], v[60:63]
	v_mfma_f32_16x16x32_bf16 v[56:59], v[158:161], v[182:185], v[56:59]
	v_mfma_f32_16x16x32_bf16 v[44:47], v[144:147], v[190:193], v[44:47]
	v_mfma_f32_16x16x32_bf16 v[40:43], v[158:161], v[190:193], v[40:43]
	v_mfma_f32_16x16x32_bf16 v[28:31], v[144:147], v[198:201], v[28:31]
	v_mfma_f32_16x16x32_bf16 v[24:27], v[158:161], v[198:201], v[24:27]
	v_mfma_f32_16x16x32_bf16 v[12:15], v[144:147], v[206:209], v[12:15]
	v_mfma_f32_16x16x32_bf16 v[8:11], v[158:161], v[206:209], v[8:11]
	v_mfma_f32_16x16x32_bf16 v[60:63], v[154:157], v[186:189], v[60:63]
	v_mfma_f32_16x16x32_bf16 v[56:59], v[162:165], v[186:189], v[56:59]
	v_mfma_f32_16x16x32_bf16 v[44:47], v[154:157], v[194:197], v[44:47]
	v_mfma_f32_16x16x32_bf16 v[40:43], v[162:165], v[194:197], v[40:43]
	v_mfma_f32_16x16x32_bf16 v[28:31], v[154:157], v[202:205], v[28:31]
	v_mfma_f32_16x16x32_bf16 v[24:27], v[162:165], v[202:205], v[24:27]
	v_mfma_f32_16x16x32_bf16 v[12:15], v[154:157], v[210:213], v[12:15]
	v_mfma_f32_16x16x32_bf16 v[8:11], v[162:165], v[210:213], v[8:11]
	v_mfma_f32_16x16x32_bf16 v[52:55], v[166:169], v[182:185], v[52:55]
	v_mfma_f32_16x16x32_bf16 v[48:51], v[174:177], v[182:185], v[48:51]
	v_mfma_f32_16x16x32_bf16 v[36:39], v[166:169], v[190:193], v[36:39]
	v_mfma_f32_16x16x32_bf16 v[32:35], v[174:177], v[190:193], v[32:35]
	v_mfma_f32_16x16x32_bf16 v[20:23], v[166:169], v[198:201], v[20:23]
	v_mfma_f32_16x16x32_bf16 v[16:19], v[174:177], v[198:201], v[16:19]
	v_mfma_f32_16x16x32_bf16 v[4:7], v[166:169], v[206:209], v[4:7]
	v_mfma_f32_16x16x32_bf16 v[0:3], v[174:177], v[206:209], v[0:3]
	v_mfma_f32_16x16x32_bf16 v[52:55], v[170:173], v[186:189], v[52:55]
	v_mfma_f32_16x16x32_bf16 v[48:51], v[178:181], v[186:189], v[48:51]
	v_mfma_f32_16x16x32_bf16 v[36:39], v[170:173], v[194:197], v[36:39]
	v_mfma_f32_16x16x32_bf16 v[32:35], v[178:181], v[194:197], v[32:35]
	v_mfma_f32_16x16x32_bf16 v[20:23], v[170:173], v[202:205], v[20:23]
	v_mfma_f32_16x16x32_bf16 v[16:19], v[178:181], v[202:205], v[16:19]
	v_mfma_f32_16x16x32_bf16 v[4:7], v[170:173], v[210:213], v[4:7]
	v_mfma_f32_16x16x32_bf16 v[0:3], v[178:181], v[210:213], v[0:3]
	s_barrier
	s_add_i32 s70, 0, 0x18000
	s_add_i32 s77, 0, 0x1c000
	v_add_u32_e32 v162, s70, v150
	v_add_u32_e32 v178, s77, v150
	ds_read_b128 v[144:147], v162
	ds_read_b128 v[154:157], v162 offset:1024
	ds_read_b128 v[158:161], v162 offset:2048
	ds_read_b128 v[162:165], v162 offset:3072
	ds_read_b128 v[166:169], v178
	ds_read_b128 v[170:173], v178 offset:1024
	ds_read_b128 v[174:177], v178 offset:2048
	ds_read_b128 v[178:181], v178 offset:3072
	s_add_u32 s50, s50, 0x40000
	s_addc_u32 s51, s51, 0
	s_mov_b32 m0, s58
	v_lshl_add_u64 v[222:223], s[50:51], 0, v[128:129]
	ds_read_b128 v[182:185], v153 offset:32768
	ds_read_b128 v[186:189], v153 offset:33792
	ds_read_b128 v[190:193], v153 offset:34816
	ds_read_b128 v[194:197], v153 offset:35840
	ds_read_b128 v[198:201], v153 offset:36864
	ds_read_b128 v[202:205], v153 offset:37888
	ds_read_b128 v[206:209], v153 offset:38912
	ds_read_b128 v[210:213], v153 offset:39936
	global_load_lds_dwordx4 v[222:223], off
	v_lshl_add_u64 v[222:223], s[50:51], 0, v[132:133]
	s_mov_b32 m0, s59
	s_nop 0
	global_load_lds_dwordx4 v[222:223], off
	s_waitcnt vmcnt(8)
	s_waitcnt lgkmcnt(0)
	s_barrier
	s_waitcnt lgkmcnt(0)
	v_mfma_f32_16x16x32_bf16 v[124:127], v[144:147], v[182:185], v[124:127]
	v_mfma_f32_16x16x32_bf16 v[120:123], v[158:161], v[182:185], v[120:123]
	v_mfma_f32_16x16x32_bf16 v[108:111], v[144:147], v[190:193], v[108:111]
	v_mfma_f32_16x16x32_bf16 v[104:107], v[158:161], v[190:193], v[104:107]
	v_mfma_f32_16x16x32_bf16 v[92:95], v[144:147], v[198:201], v[92:95]
	v_mfma_f32_16x16x32_bf16 v[88:91], v[158:161], v[198:201], v[88:91]
	v_mfma_f32_16x16x32_bf16 v[76:79], v[144:147], v[206:209], v[76:79]
	v_mfma_f32_16x16x32_bf16 v[72:75], v[158:161], v[206:209], v[72:75]
	v_mfma_f32_16x16x32_bf16 v[124:127], v[154:157], v[186:189], v[124:127]
	v_mfma_f32_16x16x32_bf16 v[120:123], v[162:165], v[186:189], v[120:123]
	v_mfma_f32_16x16x32_bf16 v[108:111], v[154:157], v[194:197], v[108:111]
	v_mfma_f32_16x16x32_bf16 v[104:107], v[162:165], v[194:197], v[104:107]
	v_mfma_f32_16x16x32_bf16 v[92:95], v[154:157], v[202:205], v[92:95]
	v_mfma_f32_16x16x32_bf16 v[88:91], v[162:165], v[202:205], v[88:91]
	v_mfma_f32_16x16x32_bf16 v[76:79], v[154:157], v[210:213], v[76:79]
	v_mfma_f32_16x16x32_bf16 v[72:75], v[162:165], v[210:213], v[72:75]
	v_mfma_f32_16x16x32_bf16 v[116:119], v[166:169], v[182:185], v[116:119]
	v_mfma_f32_16x16x32_bf16 v[112:115], v[174:177], v[182:185], v[112:115]
	v_mfma_f32_16x16x32_bf16 v[100:103], v[166:169], v[190:193], v[100:103]
	v_mfma_f32_16x16x32_bf16 v[96:99], v[174:177], v[190:193], v[96:99]
	v_mfma_f32_16x16x32_bf16 v[84:87], v[166:169], v[198:201], v[84:87]
	v_mfma_f32_16x16x32_bf16 v[80:83], v[174:177], v[198:201], v[80:83]
	v_mfma_f32_16x16x32_bf16 v[68:71], v[166:169], v[206:209], v[68:71]
	v_mfma_f32_16x16x32_bf16 v[64:67], v[174:177], v[206:209], v[64:67]
	v_mfma_f32_16x16x32_bf16 v[116:119], v[170:173], v[186:189], v[116:119]
	v_mfma_f32_16x16x32_bf16 v[112:115], v[178:181], v[186:189], v[112:115]
	v_mfma_f32_16x16x32_bf16 v[100:103], v[170:173], v[194:197], v[100:103]
	v_mfma_f32_16x16x32_bf16 v[96:99], v[178:181], v[194:197], v[96:99]
	v_mfma_f32_16x16x32_bf16 v[84:87], v[170:173], v[202:205], v[84:87]
	v_mfma_f32_16x16x32_bf16 v[80:83], v[178:181], v[202:205], v[80:83]
	v_mfma_f32_16x16x32_bf16 v[68:71], v[170:173], v[210:213], v[68:71]
	v_mfma_f32_16x16x32_bf16 v[64:67], v[178:181], v[210:213], v[64:67]
	s_barrier
	s_add_i32 s50, s70, s56
	v_lshl_add_u64 v[214:215], v[214:215], 0, s[22:23]
	s_mov_b32 m0, s50
	ds_read_b128 v[182:185], v153 offset:49152
	ds_read_b128 v[186:189], v153 offset:50176
	ds_read_b128 v[190:193], v153 offset:51200
	ds_read_b128 v[194:197], v153 offset:52224
	ds_read_b128 v[198:201], v153 offset:53248
	ds_read_b128 v[202:205], v153 offset:54272
	ds_read_b128 v[206:209], v153 offset:55296
	ds_read_b128 v[210:213], v153 offset:56320
	global_load_lds_dwordx4 v[214:215], off
	s_add_i32 m0, s50, 0x2000
	s_add_u32 s48, s48, 0x40080
	v_lshl_add_u64 v[214:215], v[216:217], 0, s[22:23]
	s_addc_u32 s49, s49, 0
	s_add_i32 s50, s77, s56
	global_load_lds_dwordx4 v[214:215], off
	v_lshl_add_u64 v[214:215], s[48:49], 0, v[130:131]
	s_mov_b32 m0, s50
	s_nop 0
	global_load_lds_dwordx4 v[214:215], off
	v_lshl_add_u64 v[214:215], s[48:49], 0, v[134:135]
	s_add_i32 m0, s50, 0x2000
	s_nop 0
	global_load_lds_dwordx4 v[214:215], off
	v_lshl_add_u64 v[214:215], v[218:219], 0, s[22:23]
	s_mov_b32 m0, s63
	s_nop 0
	global_load_lds_dwordx4 v[214:215], off
	v_lshl_add_u64 v[214:215], v[220:221], 0, s[22:23]
	s_mov_b32 m0, s64
	s_nop 0
	global_load_lds_dwordx4 v[214:215], off
	s_waitcnt vmcnt(8)
	s_waitcnt lgkmcnt(0)
	s_barrier
	s_waitcnt lgkmcnt(0)
	v_mfma_f32_16x16x32_bf16 v[60:63], v[144:147], v[182:185], v[60:63]
	v_mfma_f32_16x16x32_bf16 v[56:59], v[158:161], v[182:185], v[56:59]
	v_mfma_f32_16x16x32_bf16 v[44:47], v[144:147], v[190:193], v[44:47]
	v_mfma_f32_16x16x32_bf16 v[40:43], v[158:161], v[190:193], v[40:43]
	v_mfma_f32_16x16x32_bf16 v[28:31], v[144:147], v[198:201], v[28:31]
	v_mfma_f32_16x16x32_bf16 v[24:27], v[158:161], v[198:201], v[24:27]
	v_mfma_f32_16x16x32_bf16 v[12:15], v[144:147], v[206:209], v[12:15]
	v_mfma_f32_16x16x32_bf16 v[8:11], v[158:161], v[206:209], v[8:11]
	v_mfma_f32_16x16x32_bf16 v[60:63], v[154:157], v[186:189], v[60:63]
	v_mfma_f32_16x16x32_bf16 v[56:59], v[162:165], v[186:189], v[56:59]
	v_mfma_f32_16x16x32_bf16 v[44:47], v[154:157], v[194:197], v[44:47]
	v_mfma_f32_16x16x32_bf16 v[40:43], v[162:165], v[194:197], v[40:43]
	v_mfma_f32_16x16x32_bf16 v[28:31], v[154:157], v[202:205], v[28:31]
	v_mfma_f32_16x16x32_bf16 v[24:27], v[162:165], v[202:205], v[24:27]
	v_mfma_f32_16x16x32_bf16 v[12:15], v[154:157], v[210:213], v[12:15]
	v_mfma_f32_16x16x32_bf16 v[8:11], v[162:165], v[210:213], v[8:11]
	v_mfma_f32_16x16x32_bf16 v[52:55], v[166:169], v[182:185], v[52:55]
	v_mfma_f32_16x16x32_bf16 v[48:51], v[174:177], v[182:185], v[48:51]
	v_mfma_f32_16x16x32_bf16 v[36:39], v[166:169], v[190:193], v[36:39]
	v_mfma_f32_16x16x32_bf16 v[32:35], v[174:177], v[190:193], v[32:35]
	v_mfma_f32_16x16x32_bf16 v[20:23], v[166:169], v[198:201], v[20:23]
	v_mfma_f32_16x16x32_bf16 v[16:19], v[174:177], v[198:201], v[16:19]
	v_mfma_f32_16x16x32_bf16 v[4:7], v[166:169], v[206:209], v[4:7]
	v_mfma_f32_16x16x32_bf16 v[0:3], v[174:177], v[206:209], v[0:3]
	v_mfma_f32_16x16x32_bf16 v[52:55], v[170:173], v[186:189], v[52:55]
	v_mfma_f32_16x16x32_bf16 v[48:51], v[178:181], v[186:189], v[48:51]
	v_mfma_f32_16x16x32_bf16 v[36:39], v[170:173], v[194:197], v[36:39]
	v_mfma_f32_16x16x32_bf16 v[32:35], v[178:181], v[194:197], v[32:35]
	v_mfma_f32_16x16x32_bf16 v[20:23], v[170:173], v[202:205], v[20:23]
	v_mfma_f32_16x16x32_bf16 v[16:19], v[178:181], v[202:205], v[16:19]
	v_mfma_f32_16x16x32_bf16 v[4:7], v[170:173], v[210:213], v[4:7]
	v_mfma_f32_16x16x32_bf16 v[0:3], v[178:181], v[210:213], v[0:3]
	s_barrier
	s_add_i32 s71, s71, 2
	s_add_u32 s68, s68, 0x100
	s_addc_u32 s69, s69, 0
	s_add_u32 s46, s46, 0x100
	s_addc_u32 s47, s47, 0
	s_cmp_gt_u32 s71, 13
	s_cbranch_scc0 .LBB0_1603
	s_and_b64 vcc, exec, s[36:37]
	s_cbranch_vccz .LBB0_1606
	s_barrier

.LBB0_1719:
	ds_read_b128 v[146:149], v226
	ds_read_b128 v[150:153], v226 offset:1024
	ds_read_b128 v[154:157], v226 offset:2048
	ds_read_b128 v[158:161], v226 offset:3072
	ds_read_b128 v[162:165], v227
	ds_read_b128 v[166:169], v227 offset:1024
	ds_read_b128 v[170:173], v227 offset:2048
	ds_read_b128 v[174:177], v227 offset:3072
	s_add_u32 s52, s10, 0xfffc2080
	s_addc_u32 s53, s11, -1
	s_cmp_eq_u32 s82, 12
	s_cselect_b32 s55, s49, s53
	s_cselect_b32 s54, s48, s52
	s_cselect_b32 s53, s27, s81
	s_cselect_b32 s52, s47, s71
	v_lshl_add_u64 v[210:211], s[10:11], 0, v[138:139]
	s_add_i32 m0, s59, 0xc000
	ds_read_b128 v[178:181], v228
	ds_read_b128 v[182:185], v228 offset:1024
	ds_read_b128 v[186:189], v228 offset:2048
	ds_read_b128 v[190:193], v228 offset:3072
	ds_read_b128 v[194:197], v228 offset:4096
	ds_read_b128 v[198:201], v228 offset:5120
	ds_read_b128 v[202:205], v228 offset:6144
	ds_read_b128 v[206:209], v228 offset:7168
	global_load_lds_dwordx4 v[210:211], off
	v_lshl_add_u64 v[210:211], s[10:11], 0, v[136:137]
	s_add_i32 m0, s59, 0xe000
	s_nop 0
	global_load_lds_dwordx4 v[210:211], off
	s_waitcnt vmcnt(8)
	s_waitcnt lgkmcnt(0)
	s_barrier
	s_waitcnt lgkmcnt(0)
	v_mfma_f32_16x16x32_bf16 v[124:127], v[146:149], v[178:181], v[124:127]
	v_mfma_f32_16x16x32_bf16 v[120:123], v[154:157], v[178:181], v[120:123]
	v_mfma_f32_16x16x32_bf16 v[116:119], v[146:149], v[186:189], v[116:119]
	v_mfma_f32_16x16x32_bf16 v[108:111], v[154:157], v[186:189], v[108:111]
	v_mfma_f32_16x16x32_bf16 v[100:103], v[146:149], v[194:197], v[100:103]
	v_mfma_f32_16x16x32_bf16 v[96:99], v[154:157], v[194:197], v[96:99]
	v_mfma_f32_16x16x32_bf16 v[84:87], v[146:149], v[202:205], v[84:87]
	v_mfma_f32_16x16x32_bf16 v[76:79], v[154:157], v[202:205], v[76:79]
	v_mfma_f32_16x16x32_bf16 v[124:127], v[150:153], v[182:185], v[124:127]
	v_mfma_f32_16x16x32_bf16 v[120:123], v[158:161], v[182:185], v[120:123]
	v_mfma_f32_16x16x32_bf16 v[116:119], v[150:153], v[190:193], v[116:119]
	v_mfma_f32_16x16x32_bf16 v[108:111], v[158:161], v[190:193], v[108:111]
	v_mfma_f32_16x16x32_bf16 v[100:103], v[150:153], v[198:201], v[100:103]
	v_mfma_f32_16x16x32_bf16 v[96:99], v[158:161], v[198:201], v[96:99]
	v_mfma_f32_16x16x32_bf16 v[84:87], v[150:153], v[206:209], v[84:87]
	v_mfma_f32_16x16x32_bf16 v[76:79], v[158:161], v[206:209], v[76:79]
	v_mfma_f32_16x16x32_bf16 v[112:115], v[162:165], v[178:181], v[112:115]
	v_mfma_f32_16x16x32_bf16 v[104:107], v[170:173], v[178:181], v[104:107]
	v_mfma_f32_16x16x32_bf16 v[92:95], v[162:165], v[186:189], v[92:95]
	v_mfma_f32_16x16x32_bf16 v[88:91], v[170:173], v[186:189], v[88:91]
	v_mfma_f32_16x16x32_bf16 v[80:83], v[162:165], v[194:197], v[80:83]
	v_mfma_f32_16x16x32_bf16 v[72:75], v[170:173], v[194:197], v[72:75]
	v_mfma_f32_16x16x32_bf16 v[68:71], v[162:165], v[202:205], v[68:71]
	v_mfma_f32_16x16x32_bf16 v[64:67], v[170:173], v[202:205], v[64:67]
	v_mfma_f32_16x16x32_bf16 v[112:115], v[166:169], v[182:185], v[112:115]
	v_mfma_f32_16x16x32_bf16 v[104:107], v[174:177], v[182:185], v[104:107]
	v_mfma_f32_16x16x32_bf16 v[92:95], v[166:169], v[190:193], v[92:95]
	v_mfma_f32_16x16x32_bf16 v[88:91], v[174:177], v[190:193], v[88:91]
	v_mfma_f32_16x16x32_bf16 v[80:83], v[166:169], v[198:201], v[80:83]
	v_mfma_f32_16x16x32_bf16 v[72:75], v[174:177], v[198:201], v[72:75]
	v_mfma_f32_16x16x32_bf16 v[68:71], v[166:169], v[206:209], v[68:71]
	v_mfma_f32_16x16x32_bf16 v[64:67], v[174:177], v[206:209], v[64:67]
	s_barrier
	s_add_i32 s70, s69, s43
	v_lshl_add_u64 v[210:211], s[52:53], 0, v[130:131]
	s_mov_b32 m0, s70
	ds_read_b128 v[178:181], v228 offset:16384
	ds_read_b128 v[182:185], v228 offset:17408
	ds_read_b128 v[186:189], v228 offset:18432
	ds_read_b128 v[190:193], v228 offset:19456
	ds_read_b128 v[194:197], v228 offset:20480
	ds_read_b128 v[198:201], v228 offset:21504
	ds_read_b128 v[202:205], v228 offset:22528
	ds_read_b128 v[206:209], v228 offset:23552
	global_load_lds_dwordx4 v[210:211], off
	s_add_i32 m0, s70, 0x2000
	s_add_u32 s84, s52, 0x40000
	v_lshl_add_u64 v[212:213], s[52:53], 0, v[134:135]
	s_addc_u32 s85, s53, 0
	s_add_i32 s70, s75, s43
	global_load_lds_dwordx4 v[212:213], off
	v_lshl_add_u64 v[214:215], s[84:85], 0, v[130:131]
	s_mov_b32 m0, s70
	v_lshl_add_u64 v[216:217], s[54:55], 0, v[132:133]
	global_load_lds_dwordx4 v[214:215], off
	v_lshl_add_u64 v[214:215], s[84:85], 0, v[134:135]
	s_add_i32 m0, s70, 0x2000
	s_nop 0
	global_load_lds_dwordx4 v[214:215], off
	v_lshl_add_u64 v[214:215], s[54:55], 0, v[128:129]
	s_mov_b32 m0, s59
	s_nop 0
	global_load_lds_dwordx4 v[214:215], off
	s_mov_b32 m0, s60
	s_nop 0
	global_load_lds_dwordx4 v[216:217], off
	s_waitcnt vmcnt(8)
	s_waitcnt lgkmcnt(0)
	s_barrier
	s_waitcnt lgkmcnt(0)
	v_mfma_f32_16x16x32_bf16 v[60:63], v[146:149], v[178:181], v[60:63]
	v_mfma_f32_16x16x32_bf16 v[56:59], v[154:157], v[178:181], v[56:59]
	v_mfma_f32_16x16x32_bf16 v[52:55], v[146:149], v[186:189], v[52:55]
	v_mfma_f32_16x16x32_bf16 v[44:47], v[154:157], v[186:189], v[44:47]
	v_mfma_f32_16x16x32_bf16 v[36:39], v[146:149], v[194:197], v[36:39]
	v_mfma_f32_16x16x32_bf16 v[32:35], v[154:157], v[194:197], v[32:35]
	v_mfma_f32_16x16x32_bf16 v[20:23], v[146:149], v[202:205], v[20:23]
	v_mfma_f32_16x16x32_bf16 v[12:15], v[154:157], v[202:205], v[12:15]
	v_mfma_f32_16x16x32_bf16 v[60:63], v[150:153], v[182:185], v[60:63]
	v_mfma_f32_16x16x32_bf16 v[56:59], v[158:161], v[182:185], v[56:59]
	v_mfma_f32_16x16x32_bf16 v[52:55], v[150:153], v[190:193], v[52:55]
	v_mfma_f32_16x16x32_bf16 v[44:47], v[158:161], v[190:193], v[44:47]
	v_mfma_f32_16x16x32_bf16 v[36:39], v[150:153], v[198:201], v[36:39]
	v_mfma_f32_16x16x32_bf16 v[32:35], v[158:161], v[198:201], v[32:35]
	v_mfma_f32_16x16x32_bf16 v[20:23], v[150:153], v[206:209], v[20:23]
	v_mfma_f32_16x16x32_bf16 v[12:15], v[158:161], v[206:209], v[12:15]
	v_mfma_f32_16x16x32_bf16 v[48:51], v[162:165], v[178:181], v[48:51]
	v_mfma_f32_16x16x32_bf16 v[40:43], v[170:173], v[178:181], v[40:43]
	v_mfma_f32_16x16x32_bf16 v[28:31], v[162:165], v[186:189], v[28:31]
	v_mfma_f32_16x16x32_bf16 v[24:27], v[170:173], v[186:189], v[24:27]
	v_mfma_f32_16x16x32_bf16 v[16:19], v[162:165], v[194:197], v[16:19]
	v_mfma_f32_16x16x32_bf16 v[8:11], v[170:173], v[194:197], v[8:11]
	v_mfma_f32_16x16x32_bf16 v[4:7], v[162:165], v[202:205], v[4:7]
	v_mfma_f32_16x16x32_bf16 v[0:3], v[170:173], v[202:205], v[0:3]
	v_mfma_f32_16x16x32_bf16 v[48:51], v[166:169], v[182:185], v[48:51]
	v_mfma_f32_16x16x32_bf16 v[40:43], v[174:177], v[182:185], v[40:43]
	v_mfma_f32_16x16x32_bf16 v[28:31], v[166:169], v[190:193], v[28:31]
	v_mfma_f32_16x16x32_bf16 v[24:27], v[174:177], v[190:193], v[24:27]
	v_mfma_f32_16x16x32_bf16 v[16:19], v[166:169], v[198:201], v[16:19]
	v_mfma_f32_16x16x32_bf16 v[8:11], v[174:177], v[198:201], v[8:11]
	v_mfma_f32_16x16x32_bf16 v[4:7], v[166:169], v[206:209], v[4:7]
	v_mfma_f32_16x16x32_bf16 v[0:3], v[174:177], v[206:209], v[0:3]
	s_barrier
	s_add_i32 s70, 0, 0x18000
	s_add_i32 s83, 0, 0x1c000
	v_add_u32_e32 v158, s70, v225
	v_add_u32_e32 v174, s83, v225
	ds_read_b128 v[146:149], v158
	ds_read_b128 v[150:153], v158 offset:1024
	ds_read_b128 v[154:157], v158 offset:2048
	ds_read_b128 v[158:161], v158 offset:3072
	ds_read_b128 v[162:165], v174
	ds_read_b128 v[166:169], v174 offset:1024
	ds_read_b128 v[170:173], v174 offset:2048
	ds_read_b128 v[174:177], v174 offset:3072
	s_add_u32 s54, s54, 0x3e000
	s_addc_u32 s55, s55, 0
	s_mov_b32 m0, s61
	v_lshl_add_u64 v[218:219], s[54:55], 0, v[128:129]
	ds_read_b128 v[178:181], v228 offset:32768
	ds_read_b128 v[182:185], v228 offset:33792
	ds_read_b128 v[186:189], v228 offset:34816
	ds_read_b128 v[190:193], v228 offset:35840
	ds_read_b128 v[194:197], v228 offset:36864
	ds_read_b128 v[198:201], v228 offset:37888
	ds_read_b128 v[202:205], v228 offset:38912
	ds_read_b128 v[206:209], v228 offset:39936
	global_load_lds_dwordx4 v[218:219], off
	v_lshl_add_u64 v[218:219], s[54:55], 0, v[132:133]
	s_mov_b32 m0, s62
	s_nop 0
	global_load_lds_dwordx4 v[218:219], off
	s_waitcnt vmcnt(8)
	s_waitcnt lgkmcnt(0)
	s_barrier
	s_waitcnt lgkmcnt(0)
	v_mfma_f32_16x16x32_bf16 v[124:127], v[146:149], v[178:181], v[124:127]
	v_mfma_f32_16x16x32_bf16 v[120:123], v[154:157], v[178:181], v[120:123]
	v_mfma_f32_16x16x32_bf16 v[116:119], v[146:149], v[186:189], v[116:119]
	v_mfma_f32_16x16x32_bf16 v[108:111], v[154:157], v[186:189], v[108:111]
	v_mfma_f32_16x16x32_bf16 v[100:103], v[146:149], v[194:197], v[100:103]
	v_mfma_f32_16x16x32_bf16 v[96:99], v[154:157], v[194:197], v[96:99]
	v_mfma_f32_16x16x32_bf16 v[84:87], v[146:149], v[202:205], v[84:87]
	v_mfma_f32_16x16x32_bf16 v[76:79], v[154:157], v[202:205], v[76:79]
	v_mfma_f32_16x16x32_bf16 v[124:127], v[150:153], v[182:185], v[124:127]
	v_mfma_f32_16x16x32_bf16 v[120:123], v[158:161], v[182:185], v[120:123]
	v_mfma_f32_16x16x32_bf16 v[116:119], v[150:153], v[190:193], v[116:119]
	v_mfma_f32_16x16x32_bf16 v[108:111], v[158:161], v[190:193], v[108:111]
	v_mfma_f32_16x16x32_bf16 v[100:103], v[150:153], v[198:201], v[100:103]
	v_mfma_f32_16x16x32_bf16 v[96:99], v[158:161], v[198:201], v[96:99]
	v_mfma_f32_16x16x32_bf16 v[84:87], v[150:153], v[206:209], v[84:87]
	v_mfma_f32_16x16x32_bf16 v[76:79], v[158:161], v[206:209], v[76:79]
	v_mfma_f32_16x16x32_bf16 v[112:115], v[162:165], v[178:181], v[112:115]
	v_mfma_f32_16x16x32_bf16 v[104:107], v[170:173], v[178:181], v[104:107]
	v_mfma_f32_16x16x32_bf16 v[92:95], v[162:165], v[186:189], v[92:95]
	v_mfma_f32_16x16x32_bf16 v[88:91], v[170:173], v[186:189], v[88:91]
	v_mfma_f32_16x16x32_bf16 v[80:83], v[162:165], v[194:197], v[80:83]
	v_mfma_f32_16x16x32_bf16 v[72:75], v[170:173], v[194:197], v[72:75]
	v_mfma_f32_16x16x32_bf16 v[68:71], v[162:165], v[202:205], v[68:71]
	v_mfma_f32_16x16x32_bf16 v[64:67], v[170:173], v[202:205], v[64:67]
	v_mfma_f32_16x16x32_bf16 v[112:115], v[166:169], v[182:185], v[112:115]
	v_mfma_f32_16x16x32_bf16 v[104:107], v[174:177], v[182:185], v[104:107]
	v_mfma_f32_16x16x32_bf16 v[92:95], v[166:169], v[190:193], v[92:95]
	v_mfma_f32_16x16x32_bf16 v[88:91], v[174:177], v[190:193], v[88:91]
	v_mfma_f32_16x16x32_bf16 v[80:83], v[166:169], v[198:201], v[80:83]
	v_mfma_f32_16x16x32_bf16 v[72:75], v[174:177], v[198:201], v[72:75]
	v_mfma_f32_16x16x32_bf16 v[68:71], v[166:169], v[206:209], v[68:71]
	v_mfma_f32_16x16x32_bf16 v[64:67], v[174:177], v[206:209], v[64:67]
	s_barrier
	s_add_i32 s54, s70, s43
	v_lshl_add_u64 v[210:211], v[210:211], 0, s[36:37]
	s_mov_b32 m0, s54
	ds_read_b128 v[178:181], v228 offset:49152
	ds_read_b128 v[182:185], v228 offset:50176
	ds_read_b128 v[186:189], v228 offset:51200
	ds_read_b128 v[190:193], v228 offset:52224
	ds_read_b128 v[194:197], v228 offset:53248
	ds_read_b128 v[198:201], v228 offset:54272
	ds_read_b128 v[202:205], v228 offset:55296
	ds_read_b128 v[206:209], v228 offset:56320
	global_load_lds_dwordx4 v[210:211], off
	s_add_i32 m0, s54, 0x2000
	s_add_u32 s52, s52, 0x40080
	v_lshl_add_u64 v[210:211], v[212:213], 0, s[36:37]
	s_addc_u32 s53, s53, 0
	s_add_i32 s54, s83, s43
	global_load_lds_dwordx4 v[210:211], off
	v_lshl_add_u64 v[210:211], s[52:53], 0, v[130:131]
	s_mov_b32 m0, s54
	s_nop 0
	global_load_lds_dwordx4 v[210:211], off
	v_lshl_add_u64 v[210:211], s[52:53], 0, v[134:135]
	s_add_i32 m0, s54, 0x2000
	s_nop 0
	global_load_lds_dwordx4 v[210:211], off
	v_lshl_add_u64 v[210:211], v[214:215], 0, s[36:37]
	s_mov_b32 m0, s64
	s_nop 0
	global_load_lds_dwordx4 v[210:211], off
	v_lshl_add_u64 v[210:211], v[216:217], 0, s[36:37]
	s_mov_b32 m0, s65
	s_nop 0
	global_load_lds_dwordx4 v[210:211], off
	s_waitcnt vmcnt(8)
	s_waitcnt lgkmcnt(0)
	s_barrier
	s_waitcnt lgkmcnt(0)
	v_mfma_f32_16x16x32_bf16 v[60:63], v[146:149], v[178:181], v[60:63]
	v_mfma_f32_16x16x32_bf16 v[56:59], v[154:157], v[178:181], v[56:59]
	v_mfma_f32_16x16x32_bf16 v[52:55], v[146:149], v[186:189], v[52:55]
	v_mfma_f32_16x16x32_bf16 v[44:47], v[154:157], v[186:189], v[44:47]
	v_mfma_f32_16x16x32_bf16 v[36:39], v[146:149], v[194:197], v[36:39]
	v_mfma_f32_16x16x32_bf16 v[32:35], v[154:157], v[194:197], v[32:35]
	v_mfma_f32_16x16x32_bf16 v[20:23], v[146:149], v[202:205], v[20:23]
	v_mfma_f32_16x16x32_bf16 v[12:15], v[154:157], v[202:205], v[12:15]
	v_mfma_f32_16x16x32_bf16 v[60:63], v[150:153], v[182:185], v[60:63]
	v_mfma_f32_16x16x32_bf16 v[56:59], v[158:161], v[182:185], v[56:59]
	v_mfma_f32_16x16x32_bf16 v[52:55], v[150:153], v[190:193], v[52:55]
	v_mfma_f32_16x16x32_bf16 v[44:47], v[158:161], v[190:193], v[44:47]
	v_mfma_f32_16x16x32_bf16 v[36:39], v[150:153], v[198:201], v[36:39]
	v_mfma_f32_16x16x32_bf16 v[32:35], v[158:161], v[198:201], v[32:35]
	v_mfma_f32_16x16x32_bf16 v[20:23], v[150:153], v[206:209], v[20:23]
	v_mfma_f32_16x16x32_bf16 v[12:15], v[158:161], v[206:209], v[12:15]
	v_mfma_f32_16x16x32_bf16 v[48:51], v[162:165], v[178:181], v[48:51]
	v_mfma_f32_16x16x32_bf16 v[40:43], v[170:173], v[178:181], v[40:43]
	v_mfma_f32_16x16x32_bf16 v[28:31], v[162:165], v[186:189], v[28:31]
	v_mfma_f32_16x16x32_bf16 v[24:27], v[170:173], v[186:189], v[24:27]
	v_mfma_f32_16x16x32_bf16 v[16:19], v[162:165], v[194:197], v[16:19]
	v_mfma_f32_16x16x32_bf16 v[8:11], v[170:173], v[194:197], v[8:11]
	v_mfma_f32_16x16x32_bf16 v[4:7], v[162:165], v[202:205], v[4:7]
	v_mfma_f32_16x16x32_bf16 v[0:3], v[170:173], v[202:205], v[0:3]
	v_mfma_f32_16x16x32_bf16 v[48:51], v[166:169], v[182:185], v[48:51]
	v_mfma_f32_16x16x32_bf16 v[40:43], v[174:177], v[182:185], v[40:43]
	v_mfma_f32_16x16x32_bf16 v[28:31], v[166:169], v[190:193], v[28:31]
	v_mfma_f32_16x16x32_bf16 v[24:27], v[174:177], v[190:193], v[24:27]
	v_mfma_f32_16x16x32_bf16 v[16:19], v[166:169], v[198:201], v[16:19]
	v_mfma_f32_16x16x32_bf16 v[8:11], v[174:177], v[198:201], v[8:11]
	v_mfma_f32_16x16x32_bf16 v[4:7], v[166:169], v[206:209], v[4:7]
	v_mfma_f32_16x16x32_bf16 v[0:3], v[174:177], v[206:209], v[0:3]
	s_barrier
	s_add_i32 s82, s82, 2
	s_add_u32 s71, s71, 0x100
	s_addc_u32 s81, s81, 0
	s_add_u32 s10, s10, 0x100
	s_addc_u32 s11, s11, 0
	s_cmp_gt_u32 s82, 13
	s_cbranch_scc0 .LBB0_1719
	s_and_b64 vcc, exec, s[38:39]
	s_cbranch_vccz .LBB0_1722
	s_barrier

.LBB0_1835:
	ds_read_b128 v[144:147], v151
	ds_read_b128 v[154:157], v151 offset:1024
	ds_read_b128 v[158:161], v151 offset:2048
	ds_read_b128 v[162:165], v151 offset:3072
	ds_read_b128 v[166:169], v152
	ds_read_b128 v[170:173], v152 offset:1024
	ds_read_b128 v[174:177], v152 offset:2048
	ds_read_b128 v[178:181], v152 offset:3072
	s_add_u32 s40, s38, 0x100
	s_addc_u32 s41, s39, 0
	s_cmp_eq_u32 s62, 40
	s_cselect_b32 s45, s11, s41
	s_cselect_b32 s44, s10, s40
	s_cselect_b32 s43, s37, s27
	s_cselect_b32 s42, s36, s26
	v_lshl_add_u64 v[214:215], s[38:39], 0, v[138:139]
	s_add_i32 m0, s48, 0xc000
	ds_read_b128 v[182:185], v153
	ds_read_b128 v[186:189], v153 offset:1024
	ds_read_b128 v[190:193], v153 offset:2048
	ds_read_b128 v[194:197], v153 offset:3072
	ds_read_b128 v[198:201], v153 offset:4096
	ds_read_b128 v[202:205], v153 offset:5120
	ds_read_b128 v[206:209], v153 offset:6144
	ds_read_b128 v[210:213], v153 offset:7168
	global_load_lds_dwordx4 v[214:215], off
	v_lshl_add_u64 v[214:215], s[38:39], 0, v[136:137]
	s_add_i32 m0, s48, 0xe000
	s_nop 0
	global_load_lds_dwordx4 v[214:215], off
	s_waitcnt vmcnt(8)
	s_waitcnt lgkmcnt(0)
	s_barrier
	s_waitcnt lgkmcnt(0)
	v_mfma_f32_16x16x32_bf16 v[124:127], v[144:147], v[182:185], v[124:127]
	v_mfma_f32_16x16x32_bf16 v[120:123], v[158:161], v[182:185], v[120:123]
	v_mfma_f32_16x16x32_bf16 v[108:111], v[144:147], v[190:193], v[108:111]
	v_mfma_f32_16x16x32_bf16 v[104:107], v[158:161], v[190:193], v[104:107]
	v_mfma_f32_16x16x32_bf16 v[92:95], v[144:147], v[198:201], v[92:95]
	v_mfma_f32_16x16x32_bf16 v[88:91], v[158:161], v[198:201], v[88:91]
	v_mfma_f32_16x16x32_bf16 v[76:79], v[144:147], v[206:209], v[76:79]
	v_mfma_f32_16x16x32_bf16 v[72:75], v[158:161], v[206:209], v[72:75]
	v_mfma_f32_16x16x32_bf16 v[124:127], v[154:157], v[186:189], v[124:127]
	v_mfma_f32_16x16x32_bf16 v[120:123], v[162:165], v[186:189], v[120:123]
	v_mfma_f32_16x16x32_bf16 v[108:111], v[154:157], v[194:197], v[108:111]
	v_mfma_f32_16x16x32_bf16 v[104:107], v[162:165], v[194:197], v[104:107]
	v_mfma_f32_16x16x32_bf16 v[92:95], v[154:157], v[202:205], v[92:95]
	v_mfma_f32_16x16x32_bf16 v[88:91], v[162:165], v[202:205], v[88:91]
	v_mfma_f32_16x16x32_bf16 v[76:79], v[154:157], v[210:213], v[76:79]
	v_mfma_f32_16x16x32_bf16 v[72:75], v[162:165], v[210:213], v[72:75]
	v_mfma_f32_16x16x32_bf16 v[116:119], v[166:169], v[182:185], v[116:119]
	v_mfma_f32_16x16x32_bf16 v[112:115], v[174:177], v[182:185], v[112:115]
	v_mfma_f32_16x16x32_bf16 v[100:103], v[166:169], v[190:193], v[100:103]
	v_mfma_f32_16x16x32_bf16 v[96:99], v[174:177], v[190:193], v[96:99]
	v_mfma_f32_16x16x32_bf16 v[84:87], v[166:169], v[198:201], v[84:87]
	v_mfma_f32_16x16x32_bf16 v[80:83], v[174:177], v[198:201], v[80:83]
	v_mfma_f32_16x16x32_bf16 v[68:71], v[166:169], v[206:209], v[68:71]
	v_mfma_f32_16x16x32_bf16 v[64:67], v[174:177], v[206:209], v[64:67]
	v_mfma_f32_16x16x32_bf16 v[116:119], v[170:173], v[186:189], v[116:119]
	v_mfma_f32_16x16x32_bf16 v[112:115], v[178:181], v[186:189], v[112:115]
	v_mfma_f32_16x16x32_bf16 v[100:103], v[170:173], v[194:197], v[100:103]
	v_mfma_f32_16x16x32_bf16 v[96:99], v[178:181], v[194:197], v[96:99]
	v_mfma_f32_16x16x32_bf16 v[84:87], v[170:173], v[202:205], v[84:87]
	v_mfma_f32_16x16x32_bf16 v[80:83], v[178:181], v[202:205], v[80:83]
	v_mfma_f32_16x16x32_bf16 v[68:71], v[170:173], v[210:213], v[68:71]
	v_mfma_f32_16x16x32_bf16 v[64:67], v[178:181], v[210:213], v[64:67]
	s_barrier
	s_add_i32 s38, s57, s47
	v_lshl_add_u64 v[214:215], s[42:43], 0, v[130:131]
	s_mov_b32 m0, s38
	ds_read_b128 v[182:185], v153 offset:16384
	ds_read_b128 v[186:189], v153 offset:17408
	ds_read_b128 v[190:193], v153 offset:18432
	ds_read_b128 v[194:197], v153 offset:19456
	ds_read_b128 v[198:201], v153 offset:20480
	ds_read_b128 v[202:205], v153 offset:21504
	ds_read_b128 v[206:209], v153 offset:22528
	ds_read_b128 v[210:213], v153 offset:23552
	global_load_lds_dwordx4 v[214:215], off
	s_add_i32 m0, s38, 0x2000
	s_add_u32 s38, s42, 0xb0000
	v_lshl_add_u64 v[216:217], s[42:43], 0, v[134:135]
	s_addc_u32 s39, s43, 0
	s_add_i32 s63, s58, s47
	global_load_lds_dwordx4 v[216:217], off
	v_lshl_add_u64 v[218:219], s[38:39], 0, v[130:131]
	s_mov_b32 m0, s63
	v_lshl_add_u64 v[220:221], s[44:45], 0, v[132:133]
	global_load_lds_dwordx4 v[218:219], off
	v_lshl_add_u64 v[218:219], s[38:39], 0, v[134:135]
	s_add_i32 m0, s63, 0x2000
	s_nop 0
	global_load_lds_dwordx4 v[218:219], off
	v_lshl_add_u64 v[218:219], s[44:45], 0, v[128:129]
	s_mov_b32 m0, s48
	s_nop 0
	global_load_lds_dwordx4 v[218:219], off
	s_mov_b32 m0, s49
	s_nop 0
	global_load_lds_dwordx4 v[220:221], off
	s_waitcnt vmcnt(8)
	s_waitcnt lgkmcnt(0)
	s_barrier
	s_waitcnt lgkmcnt(0)
	v_mfma_f32_16x16x32_bf16 v[60:63], v[144:147], v[182:185], v[60:63]
	v_mfma_f32_16x16x32_bf16 v[56:59], v[158:161], v[182:185], v[56:59]
	v_mfma_f32_16x16x32_bf16 v[44:47], v[144:147], v[190:193], v[44:47]
	v_mfma_f32_16x16x32_bf16 v[40:43], v[158:161], v[190:193], v[40:43]
	v_mfma_f32_16x16x32_bf16 v[28:31], v[144:147], v[198:201], v[28:31]
	v_mfma_f32_16x16x32_bf16 v[24:27], v[158:161], v[198:201], v[24:27]
	v_mfma_f32_16x16x32_bf16 v[12:15], v[144:147], v[206:209], v[12:15]
	v_mfma_f32_16x16x32_bf16 v[8:11], v[158:161], v[206:209], v[8:11]
	v_mfma_f32_16x16x32_bf16 v[60:63], v[154:157], v[186:189], v[60:63]
	v_mfma_f32_16x16x32_bf16 v[56:59], v[162:165], v[186:189], v[56:59]
	v_mfma_f32_16x16x32_bf16 v[44:47], v[154:157], v[194:197], v[44:47]
	v_mfma_f32_16x16x32_bf16 v[40:43], v[162:165], v[194:197], v[40:43]
	v_mfma_f32_16x16x32_bf16 v[28:31], v[154:157], v[202:205], v[28:31]
	v_mfma_f32_16x16x32_bf16 v[24:27], v[162:165], v[202:205], v[24:27]
	v_mfma_f32_16x16x32_bf16 v[12:15], v[154:157], v[210:213], v[12:15]
	v_mfma_f32_16x16x32_bf16 v[8:11], v[162:165], v[210:213], v[8:11]
	v_mfma_f32_16x16x32_bf16 v[52:55], v[166:169], v[182:185], v[52:55]
	v_mfma_f32_16x16x32_bf16 v[48:51], v[174:177], v[182:185], v[48:51]
	v_mfma_f32_16x16x32_bf16 v[36:39], v[166:169], v[190:193], v[36:39]
	v_mfma_f32_16x16x32_bf16 v[32:35], v[174:177], v[190:193], v[32:35]
	v_mfma_f32_16x16x32_bf16 v[20:23], v[166:169], v[198:201], v[20:23]
	v_mfma_f32_16x16x32_bf16 v[16:19], v[174:177], v[198:201], v[16:19]
	v_mfma_f32_16x16x32_bf16 v[4:7], v[166:169], v[206:209], v[4:7]
	v_mfma_f32_16x16x32_bf16 v[0:3], v[174:177], v[206:209], v[0:3]
	v_mfma_f32_16x16x32_bf16 v[52:55], v[170:173], v[186:189], v[52:55]
	v_mfma_f32_16x16x32_bf16 v[48:51], v[178:181], v[186:189], v[48:51]
	v_mfma_f32_16x16x32_bf16 v[36:39], v[170:173], v[194:197], v[36:39]
	v_mfma_f32_16x16x32_bf16 v[32:35], v[178:181], v[194:197], v[32:35]
	v_mfma_f32_16x16x32_bf16 v[20:23], v[170:173], v[202:205], v[20:23]
	v_mfma_f32_16x16x32_bf16 v[16:19], v[178:181], v[202:205], v[16:19]
	v_mfma_f32_16x16x32_bf16 v[4:7], v[170:173], v[210:213], v[4:7]
	v_mfma_f32_16x16x32_bf16 v[0:3], v[178:181], v[210:213], v[0:3]
	s_barrier
	s_add_i32 s63, 0, 0x18000
	s_add_i32 s64, 0, 0x1c000
	v_add_u32_e32 v162, s63, v150
	v_add_u32_e32 v178, s64, v150
	ds_read_b128 v[144:147], v162
	ds_read_b128 v[154:157], v162 offset:1024
	ds_read_b128 v[158:161], v162 offset:2048
	ds_read_b128 v[162:165], v162 offset:3072
	ds_read_b128 v[166:169], v178
	ds_read_b128 v[170:173], v178 offset:1024
	ds_read_b128 v[174:177], v178 offset:2048
	ds_read_b128 v[178:181], v178 offset:3072
	s_add_u32 s38, s44, 0xb0000
	s_addc_u32 s39, s45, 0
	s_mov_b32 m0, s50
	v_lshl_add_u64 v[222:223], s[38:39], 0, v[128:129]
	ds_read_b128 v[182:185], v153 offset:32768
	ds_read_b128 v[186:189], v153 offset:33792
	ds_read_b128 v[190:193], v153 offset:34816
	ds_read_b128 v[194:197], v153 offset:35840
	ds_read_b128 v[198:201], v153 offset:36864
	ds_read_b128 v[202:205], v153 offset:37888
	ds_read_b128 v[206:209], v153 offset:38912
	ds_read_b128 v[210:213], v153 offset:39936
	global_load_lds_dwordx4 v[222:223], off
	v_lshl_add_u64 v[222:223], s[38:39], 0, v[132:133]
	s_mov_b32 m0, s51
	s_nop 0
	global_load_lds_dwordx4 v[222:223], off
	s_waitcnt vmcnt(8)
	s_waitcnt lgkmcnt(0)
	s_barrier
	s_waitcnt lgkmcnt(0)
	v_mfma_f32_16x16x32_bf16 v[124:127], v[144:147], v[182:185], v[124:127]
	v_mfma_f32_16x16x32_bf16 v[120:123], v[158:161], v[182:185], v[120:123]
	v_mfma_f32_16x16x32_bf16 v[108:111], v[144:147], v[190:193], v[108:111]
	v_mfma_f32_16x16x32_bf16 v[104:107], v[158:161], v[190:193], v[104:107]
	v_mfma_f32_16x16x32_bf16 v[92:95], v[144:147], v[198:201], v[92:95]
	v_mfma_f32_16x16x32_bf16 v[88:91], v[158:161], v[198:201], v[88:91]
	v_mfma_f32_16x16x32_bf16 v[76:79], v[144:147], v[206:209], v[76:79]
	v_mfma_f32_16x16x32_bf16 v[72:75], v[158:161], v[206:209], v[72:75]
	v_mfma_f32_16x16x32_bf16 v[124:127], v[154:157], v[186:189], v[124:127]
	v_mfma_f32_16x16x32_bf16 v[120:123], v[162:165], v[186:189], v[120:123]
	v_mfma_f32_16x16x32_bf16 v[108:111], v[154:157], v[194:197], v[108:111]
	v_mfma_f32_16x16x32_bf16 v[104:107], v[162:165], v[194:197], v[104:107]
	v_mfma_f32_16x16x32_bf16 v[92:95], v[154:157], v[202:205], v[92:95]
	v_mfma_f32_16x16x32_bf16 v[88:91], v[162:165], v[202:205], v[88:91]
	v_mfma_f32_16x16x32_bf16 v[76:79], v[154:157], v[210:213], v[76:79]
	v_mfma_f32_16x16x32_bf16 v[72:75], v[162:165], v[210:213], v[72:75]
	v_mfma_f32_16x16x32_bf16 v[116:119], v[166:169], v[182:185], v[116:119]
	v_mfma_f32_16x16x32_bf16 v[112:115], v[174:177], v[182:185], v[112:115]
	v_mfma_f32_16x16x32_bf16 v[100:103], v[166:169], v[190:193], v[100:103]
	v_mfma_f32_16x16x32_bf16 v[96:99], v[174:177], v[190:193], v[96:99]
	v_mfma_f32_16x16x32_bf16 v[84:87], v[166:169], v[198:201], v[84:87]
	v_mfma_f32_16x16x32_bf16 v[80:83], v[174:177], v[198:201], v[80:83]
	v_mfma_f32_16x16x32_bf16 v[68:71], v[166:169], v[206:209], v[68:71]
	v_mfma_f32_16x16x32_bf16 v[64:67], v[174:177], v[206:209], v[64:67]
	v_mfma_f32_16x16x32_bf16 v[116:119], v[170:173], v[186:189], v[116:119]
	v_mfma_f32_16x16x32_bf16 v[112:115], v[178:181], v[186:189], v[112:115]
	v_mfma_f32_16x16x32_bf16 v[100:103], v[170:173], v[194:197], v[100:103]
	v_mfma_f32_16x16x32_bf16 v[96:99], v[178:181], v[194:197], v[96:99]
	v_mfma_f32_16x16x32_bf16 v[84:87], v[170:173], v[202:205], v[84:87]
	v_mfma_f32_16x16x32_bf16 v[80:83], v[178:181], v[202:205], v[80:83]
	v_mfma_f32_16x16x32_bf16 v[68:71], v[170:173], v[210:213], v[68:71]
	v_mfma_f32_16x16x32_bf16 v[64:67], v[178:181], v[210:213], v[64:67]
	s_barrier
	s_add_i32 s38, s63, s47
	v_lshl_add_u64 v[214:215], v[214:215], 0, s[22:23]
	s_mov_b32 m0, s38
	ds_read_b128 v[182:185], v153 offset:49152
	ds_read_b128 v[186:189], v153 offset:50176
	ds_read_b128 v[190:193], v153 offset:51200
	ds_read_b128 v[194:197], v153 offset:52224
	ds_read_b128 v[198:201], v153 offset:53248
	ds_read_b128 v[202:205], v153 offset:54272
	ds_read_b128 v[206:209], v153 offset:55296
	ds_read_b128 v[210:213], v153 offset:56320
	global_load_lds_dwordx4 v[214:215], off
	s_add_i32 m0, s38, 0x2000
	s_add_u32 s38, s42, 0xb0080
	v_lshl_add_u64 v[214:215], v[216:217], 0, s[22:23]
	s_addc_u32 s39, s43, 0
	s_add_i32 s42, s64, s47
	global_load_lds_dwordx4 v[214:215], off
	v_lshl_add_u64 v[214:215], s[38:39], 0, v[130:131]
	s_mov_b32 m0, s42
	s_nop 0
	global_load_lds_dwordx4 v[214:215], off
	v_lshl_add_u64 v[214:215], s[38:39], 0, v[134:135]
	s_add_i32 m0, s42, 0x2000
	s_nop 0
	global_load_lds_dwordx4 v[214:215], off
	v_lshl_add_u64 v[214:215], v[218:219], 0, s[22:23]
	s_mov_b32 m0, s55
	s_nop 0
	global_load_lds_dwordx4 v[214:215], off
	v_lshl_add_u64 v[214:215], v[220:221], 0, s[22:23]
	s_mov_b32 m0, s56
	s_nop 0
	global_load_lds_dwordx4 v[214:215], off
	s_waitcnt vmcnt(8)
	s_waitcnt lgkmcnt(0)
	s_barrier
	s_waitcnt lgkmcnt(0)
	v_mfma_f32_16x16x32_bf16 v[60:63], v[144:147], v[182:185], v[60:63]
	v_mfma_f32_16x16x32_bf16 v[56:59], v[158:161], v[182:185], v[56:59]
	v_mfma_f32_16x16x32_bf16 v[44:47], v[144:147], v[190:193], v[44:47]
	v_mfma_f32_16x16x32_bf16 v[40:43], v[158:161], v[190:193], v[40:43]
	v_mfma_f32_16x16x32_bf16 v[28:31], v[144:147], v[198:201], v[28:31]
	v_mfma_f32_16x16x32_bf16 v[24:27], v[158:161], v[198:201], v[24:27]
	v_mfma_f32_16x16x32_bf16 v[12:15], v[144:147], v[206:209], v[12:15]
	v_mfma_f32_16x16x32_bf16 v[8:11], v[158:161], v[206:209], v[8:11]
	v_mfma_f32_16x16x32_bf16 v[60:63], v[154:157], v[186:189], v[60:63]
	v_mfma_f32_16x16x32_bf16 v[56:59], v[162:165], v[186:189], v[56:59]
	v_mfma_f32_16x16x32_bf16 v[44:47], v[154:157], v[194:197], v[44:47]
	v_mfma_f32_16x16x32_bf16 v[40:43], v[162:165], v[194:197], v[40:43]
	v_mfma_f32_16x16x32_bf16 v[28:31], v[154:157], v[202:205], v[28:31]
	v_mfma_f32_16x16x32_bf16 v[24:27], v[162:165], v[202:205], v[24:27]
	v_mfma_f32_16x16x32_bf16 v[12:15], v[154:157], v[210:213], v[12:15]
	v_mfma_f32_16x16x32_bf16 v[8:11], v[162:165], v[210:213], v[8:11]
	v_mfma_f32_16x16x32_bf16 v[52:55], v[166:169], v[182:185], v[52:55]
	v_mfma_f32_16x16x32_bf16 v[48:51], v[174:177], v[182:185], v[48:51]
	v_mfma_f32_16x16x32_bf16 v[36:39], v[166:169], v[190:193], v[36:39]
	v_mfma_f32_16x16x32_bf16 v[32:35], v[174:177], v[190:193], v[32:35]
	v_mfma_f32_16x16x32_bf16 v[20:23], v[166:169], v[198:201], v[20:23]
	v_mfma_f32_16x16x32_bf16 v[16:19], v[174:177], v[198:201], v[16:19]
	v_mfma_f32_16x16x32_bf16 v[4:7], v[166:169], v[206:209], v[4:7]
	v_mfma_f32_16x16x32_bf16 v[0:3], v[174:177], v[206:209], v[0:3]
	v_mfma_f32_16x16x32_bf16 v[52:55], v[170:173], v[186:189], v[52:55]
	v_mfma_f32_16x16x32_bf16 v[48:51], v[178:181], v[186:189], v[48:51]
	v_mfma_f32_16x16x32_bf16 v[36:39], v[170:173], v[194:197], v[36:39]
	v_mfma_f32_16x16x32_bf16 v[32:35], v[178:181], v[194:197], v[32:35]
	v_mfma_f32_16x16x32_bf16 v[20:23], v[170:173], v[202:205], v[20:23]
	v_mfma_f32_16x16x32_bf16 v[16:19], v[178:181], v[202:205], v[16:19]
	v_mfma_f32_16x16x32_bf16 v[4:7], v[170:173], v[210:213], v[4:7]
	v_mfma_f32_16x16x32_bf16 v[0:3], v[178:181], v[210:213], v[0:3]
	s_barrier
	s_add_i32 s62, s62, 2
	s_add_u32 s26, s26, 0x100
	s_addc_u32 s27, s27, 0
	s_cmp_gt_u32 s62, 41
	s_mov_b64 s[38:39], s[40:41]
	s_cbranch_scc0 .LBB0_1835
	s_and_b64 vcc, exec, s[34:35]
	s_cbranch_vccz .LBB0_1838
	s_barrier

.LBB0_1931:
	ds_read_b128 v[144:147], v181
	ds_read_b128 v[148:151], v181 offset:1024
	ds_read_b128 v[152:155], v181 offset:2048
	ds_read_b128 v[156:159], v181 offset:3072
	ds_read_b128 v[160:163], v182
	ds_read_b128 v[164:167], v182 offset:1024
	ds_read_b128 v[168:171], v182 offset:2048
	ds_read_b128 v[172:175], v182 offset:3072
	s_add_u32 s36, s34, 0x100
	s_addc_u32 s37, s35, 0
	s_cmp_eq_u32 s60, 40
	s_cselect_b32 s41, s7, s37
	s_cselect_b32 s40, s6, s36
	s_cselect_b32 s39, s31, s27
	s_cselect_b32 s38, s30, s16
	v_lshl_add_u64 v[176:177], s[34:35], 0, v[138:139]
	s_add_i32 m0, s42, 0xc000
	ds_read_b128 v[186:189], v183
	ds_read_b128 v[190:193], v183 offset:1024
	ds_read_b128 v[194:197], v183 offset:2048
	ds_read_b128 v[198:201], v183 offset:3072
	ds_read_b128 v[202:205], v183 offset:4096
	ds_read_b128 v[206:209], v183 offset:5120
	ds_read_b128 v[210:213], v183 offset:6144
	ds_read_b128 v[214:217], v183 offset:7168
	global_load_lds_dwordx4 v[176:177], off
	v_lshl_add_u64 v[176:177], s[34:35], 0, v[136:137]
	s_add_i32 m0, s42, 0xe000
	s_nop 0
	global_load_lds_dwordx4 v[176:177], off
	s_waitcnt vmcnt(8)
	s_waitcnt lgkmcnt(0)
	s_barrier
	s_waitcnt lgkmcnt(0)
	v_mfma_f32_16x16x32_bf16 v[124:127], v[144:147], v[186:189], v[124:127]
	v_mfma_f32_16x16x32_bf16 v[120:123], v[152:155], v[186:189], v[120:123]
	v_mfma_f32_16x16x32_bf16 v[108:111], v[144:147], v[194:197], v[108:111]
	v_mfma_f32_16x16x32_bf16 v[104:107], v[152:155], v[194:197], v[104:107]
	v_mfma_f32_16x16x32_bf16 v[92:95], v[144:147], v[202:205], v[92:95]
	v_mfma_f32_16x16x32_bf16 v[88:91], v[152:155], v[202:205], v[88:91]
	v_mfma_f32_16x16x32_bf16 v[76:79], v[144:147], v[210:213], v[76:79]
	v_mfma_f32_16x16x32_bf16 v[72:75], v[152:155], v[210:213], v[72:75]
	v_mfma_f32_16x16x32_bf16 v[124:127], v[148:151], v[190:193], v[124:127]
	v_mfma_f32_16x16x32_bf16 v[120:123], v[156:159], v[190:193], v[120:123]
	v_mfma_f32_16x16x32_bf16 v[108:111], v[148:151], v[198:201], v[108:111]
	v_mfma_f32_16x16x32_bf16 v[104:107], v[156:159], v[198:201], v[104:107]
	v_mfma_f32_16x16x32_bf16 v[92:95], v[148:151], v[206:209], v[92:95]
	v_mfma_f32_16x16x32_bf16 v[88:91], v[156:159], v[206:209], v[88:91]
	v_mfma_f32_16x16x32_bf16 v[76:79], v[148:151], v[214:217], v[76:79]
	v_mfma_f32_16x16x32_bf16 v[72:75], v[156:159], v[214:217], v[72:75]
	v_mfma_f32_16x16x32_bf16 v[116:119], v[160:163], v[186:189], v[116:119]
	v_mfma_f32_16x16x32_bf16 v[112:115], v[168:171], v[186:189], v[112:115]
	v_mfma_f32_16x16x32_bf16 v[100:103], v[160:163], v[194:197], v[100:103]
	v_mfma_f32_16x16x32_bf16 v[96:99], v[168:171], v[194:197], v[96:99]
	v_mfma_f32_16x16x32_bf16 v[84:87], v[160:163], v[202:205], v[84:87]
	v_mfma_f32_16x16x32_bf16 v[80:83], v[168:171], v[202:205], v[80:83]
	v_mfma_f32_16x16x32_bf16 v[68:71], v[160:163], v[210:213], v[68:71]
	v_mfma_f32_16x16x32_bf16 v[64:67], v[168:171], v[210:213], v[64:67]
	v_mfma_f32_16x16x32_bf16 v[116:119], v[164:167], v[190:193], v[116:119]
	v_mfma_f32_16x16x32_bf16 v[112:115], v[172:175], v[190:193], v[112:115]
	v_mfma_f32_16x16x32_bf16 v[100:103], v[164:167], v[198:201], v[100:103]
	v_mfma_f32_16x16x32_bf16 v[96:99], v[172:175], v[198:201], v[96:99]
	v_mfma_f32_16x16x32_bf16 v[84:87], v[164:167], v[206:209], v[84:87]
	v_mfma_f32_16x16x32_bf16 v[80:83], v[172:175], v[206:209], v[80:83]
	v_mfma_f32_16x16x32_bf16 v[68:71], v[164:167], v[214:217], v[68:71]
	v_mfma_f32_16x16x32_bf16 v[64:67], v[172:175], v[214:217], v[64:67]
	s_barrier
	s_add_i32 s34, s54, s25
	v_lshl_add_u64 v[176:177], s[38:39], 0, v[130:131]
	s_mov_b32 m0, s34
	ds_read_b128 v[186:189], v183 offset:16384
	ds_read_b128 v[190:193], v183 offset:17408
	ds_read_b128 v[194:197], v183 offset:18432
	ds_read_b128 v[198:201], v183 offset:19456
	ds_read_b128 v[202:205], v183 offset:20480
	ds_read_b128 v[206:209], v183 offset:21504
	ds_read_b128 v[210:213], v183 offset:22528
	ds_read_b128 v[214:217], v183 offset:23552
	global_load_lds_dwordx4 v[176:177], off
	s_add_i32 m0, s34, 0x2000
	s_add_u32 s34, s38, 0xb0000
	v_lshl_add_u64 v[218:219], s[38:39], 0, v[134:135]
	s_addc_u32 s35, s39, 0
	s_add_i32 s61, s55, s25
	global_load_lds_dwordx4 v[218:219], off
	v_lshl_add_u64 v[220:221], s[34:35], 0, v[130:131]
	s_mov_b32 m0, s61
	v_lshl_add_u64 v[222:223], s[40:41], 0, v[132:133]
	global_load_lds_dwordx4 v[220:221], off
	v_lshl_add_u64 v[220:221], s[34:35], 0, v[134:135]
	s_add_i32 m0, s61, 0x2000
	s_nop 0
	global_load_lds_dwordx4 v[220:221], off
	v_lshl_add_u64 v[220:221], s[40:41], 0, v[128:129]
	s_mov_b32 m0, s42
	s_nop 0
	global_load_lds_dwordx4 v[220:221], off
	s_mov_b32 m0, s43
	s_nop 0
	global_load_lds_dwordx4 v[222:223], off
	s_waitcnt vmcnt(8)
	s_waitcnt lgkmcnt(0)
	s_barrier
	s_waitcnt lgkmcnt(0)
	v_mfma_f32_16x16x32_bf16 v[60:63], v[144:147], v[186:189], v[60:63]
	v_mfma_f32_16x16x32_bf16 v[56:59], v[152:155], v[186:189], v[56:59]
	v_mfma_f32_16x16x32_bf16 v[44:47], v[144:147], v[194:197], v[44:47]
	v_mfma_f32_16x16x32_bf16 v[40:43], v[152:155], v[194:197], v[40:43]
	v_mfma_f32_16x16x32_bf16 v[28:31], v[144:147], v[202:205], v[28:31]
	v_mfma_f32_16x16x32_bf16 v[24:27], v[152:155], v[202:205], v[24:27]
	v_mfma_f32_16x16x32_bf16 v[12:15], v[144:147], v[210:213], v[12:15]
	v_mfma_f32_16x16x32_bf16 v[8:11], v[152:155], v[210:213], v[8:11]
	v_mfma_f32_16x16x32_bf16 v[60:63], v[148:151], v[190:193], v[60:63]
	v_mfma_f32_16x16x32_bf16 v[56:59], v[156:159], v[190:193], v[56:59]
	v_mfma_f32_16x16x32_bf16 v[44:47], v[148:151], v[198:201], v[44:47]
	v_mfma_f32_16x16x32_bf16 v[40:43], v[156:159], v[198:201], v[40:43]
	v_mfma_f32_16x16x32_bf16 v[28:31], v[148:151], v[206:209], v[28:31]
	v_mfma_f32_16x16x32_bf16 v[24:27], v[156:159], v[206:209], v[24:27]
	v_mfma_f32_16x16x32_bf16 v[12:15], v[148:151], v[214:217], v[12:15]
	v_mfma_f32_16x16x32_bf16 v[8:11], v[156:159], v[214:217], v[8:11]
	v_mfma_f32_16x16x32_bf16 v[52:55], v[160:163], v[186:189], v[52:55]
	v_mfma_f32_16x16x32_bf16 v[48:51], v[168:171], v[186:189], v[48:51]
	v_mfma_f32_16x16x32_bf16 v[36:39], v[160:163], v[194:197], v[36:39]
	v_mfma_f32_16x16x32_bf16 v[32:35], v[168:171], v[194:197], v[32:35]
	v_mfma_f32_16x16x32_bf16 v[20:23], v[160:163], v[202:205], v[20:23]
	v_mfma_f32_16x16x32_bf16 v[16:19], v[168:171], v[202:205], v[16:19]
	v_mfma_f32_16x16x32_bf16 v[4:7], v[160:163], v[210:213], v[4:7]
	v_mfma_f32_16x16x32_bf16 v[0:3], v[168:171], v[210:213], v[0:3]
	v_mfma_f32_16x16x32_bf16 v[52:55], v[164:167], v[190:193], v[52:55]
	v_mfma_f32_16x16x32_bf16 v[48:51], v[172:175], v[190:193], v[48:51]
	v_mfma_f32_16x16x32_bf16 v[36:39], v[164:167], v[198:201], v[36:39]
	v_mfma_f32_16x16x32_bf16 v[32:35], v[172:175], v[198:201], v[32:35]
	v_mfma_f32_16x16x32_bf16 v[20:23], v[164:167], v[206:209], v[20:23]
	v_mfma_f32_16x16x32_bf16 v[16:19], v[172:175], v[206:209], v[16:19]
	v_mfma_f32_16x16x32_bf16 v[4:7], v[164:167], v[214:217], v[4:7]
	v_mfma_f32_16x16x32_bf16 v[0:3], v[172:175], v[214:217], v[0:3]
	s_barrier
	s_add_i32 s61, 0, 0x18000
	s_add_i32 s62, 0, 0x1c000
	v_add_u32_e32 v156, s61, v180
	v_add_u32_e32 v172, s62, v180
	ds_read_b128 v[144:147], v156
	ds_read_b128 v[148:151], v156 offset:1024
	ds_read_b128 v[152:155], v156 offset:2048
	ds_read_b128 v[156:159], v156 offset:3072
	ds_read_b128 v[160:163], v172
	ds_read_b128 v[164:167], v172 offset:1024
	ds_read_b128 v[168:171], v172 offset:2048
	ds_read_b128 v[172:175], v172 offset:3072
	s_add_u32 s34, s40, 0xb0000
	s_addc_u32 s35, s41, 0
	s_mov_b32 m0, s44
	v_lshl_add_u64 v[226:227], s[34:35], 0, v[128:129]
	ds_read_b128 v[186:189], v183 offset:32768
	ds_read_b128 v[190:193], v183 offset:33792
	ds_read_b128 v[194:197], v183 offset:34816
	ds_read_b128 v[198:201], v183 offset:35840
	ds_read_b128 v[202:205], v183 offset:36864
	ds_read_b128 v[206:209], v183 offset:37888
	ds_read_b128 v[210:213], v183 offset:38912
	ds_read_b128 v[214:217], v183 offset:39936
	global_load_lds_dwordx4 v[226:227], off
	v_lshl_add_u64 v[226:227], s[34:35], 0, v[132:133]
	s_mov_b32 m0, s45
	s_nop 0
	global_load_lds_dwordx4 v[226:227], off
	s_waitcnt vmcnt(8)
	s_waitcnt lgkmcnt(0)
	s_barrier
	s_waitcnt lgkmcnt(0)
	v_mfma_f32_16x16x32_bf16 v[124:127], v[144:147], v[186:189], v[124:127]
	v_mfma_f32_16x16x32_bf16 v[120:123], v[152:155], v[186:189], v[120:123]
	v_mfma_f32_16x16x32_bf16 v[108:111], v[144:147], v[194:197], v[108:111]
	v_mfma_f32_16x16x32_bf16 v[104:107], v[152:155], v[194:197], v[104:107]
	v_mfma_f32_16x16x32_bf16 v[92:95], v[144:147], v[202:205], v[92:95]
	v_mfma_f32_16x16x32_bf16 v[88:91], v[152:155], v[202:205], v[88:91]
	v_mfma_f32_16x16x32_bf16 v[76:79], v[144:147], v[210:213], v[76:79]
	v_mfma_f32_16x16x32_bf16 v[72:75], v[152:155], v[210:213], v[72:75]
	v_mfma_f32_16x16x32_bf16 v[124:127], v[148:151], v[190:193], v[124:127]
	v_mfma_f32_16x16x32_bf16 v[120:123], v[156:159], v[190:193], v[120:123]
	v_mfma_f32_16x16x32_bf16 v[108:111], v[148:151], v[198:201], v[108:111]
	v_mfma_f32_16x16x32_bf16 v[104:107], v[156:159], v[198:201], v[104:107]
	v_mfma_f32_16x16x32_bf16 v[92:95], v[148:151], v[206:209], v[92:95]
	v_mfma_f32_16x16x32_bf16 v[88:91], v[156:159], v[206:209], v[88:91]
	v_mfma_f32_16x16x32_bf16 v[76:79], v[148:151], v[214:217], v[76:79]
	v_mfma_f32_16x16x32_bf16 v[72:75], v[156:159], v[214:217], v[72:75]
	v_mfma_f32_16x16x32_bf16 v[116:119], v[160:163], v[186:189], v[116:119]
	v_mfma_f32_16x16x32_bf16 v[112:115], v[168:171], v[186:189], v[112:115]
	v_mfma_f32_16x16x32_bf16 v[100:103], v[160:163], v[194:197], v[100:103]
	v_mfma_f32_16x16x32_bf16 v[96:99], v[168:171], v[194:197], v[96:99]
	v_mfma_f32_16x16x32_bf16 v[84:87], v[160:163], v[202:205], v[84:87]
	v_mfma_f32_16x16x32_bf16 v[80:83], v[168:171], v[202:205], v[80:83]
	v_mfma_f32_16x16x32_bf16 v[68:71], v[160:163], v[210:213], v[68:71]
	v_mfma_f32_16x16x32_bf16 v[64:67], v[168:171], v[210:213], v[64:67]
	v_mfma_f32_16x16x32_bf16 v[116:119], v[164:167], v[190:193], v[116:119]
	v_mfma_f32_16x16x32_bf16 v[112:115], v[172:175], v[190:193], v[112:115]
	v_mfma_f32_16x16x32_bf16 v[100:103], v[164:167], v[198:201], v[100:103]
	v_mfma_f32_16x16x32_bf16 v[96:99], v[172:175], v[198:201], v[96:99]
	v_mfma_f32_16x16x32_bf16 v[84:87], v[164:167], v[206:209], v[84:87]
	v_mfma_f32_16x16x32_bf16 v[80:83], v[172:175], v[206:209], v[80:83]
	v_mfma_f32_16x16x32_bf16 v[68:71], v[164:167], v[214:217], v[68:71]
	v_mfma_f32_16x16x32_bf16 v[64:67], v[172:175], v[214:217], v[64:67]
	s_barrier
	s_add_i32 s34, s61, s25
	v_lshl_add_u64 v[176:177], v[176:177], 0, s[20:21]
	s_mov_b32 m0, s34
	ds_read_b128 v[186:189], v183 offset:49152
	ds_read_b128 v[190:193], v183 offset:50176
	ds_read_b128 v[194:197], v183 offset:51200
	ds_read_b128 v[198:201], v183 offset:52224
	ds_read_b128 v[202:205], v183 offset:53248
	ds_read_b128 v[206:209], v183 offset:54272
	ds_read_b128 v[210:213], v183 offset:55296
	ds_read_b128 v[214:217], v183 offset:56320
	global_load_lds_dwordx4 v[176:177], off
	s_add_i32 m0, s34, 0x2000
	s_add_u32 s34, s38, 0xb0080
	v_lshl_add_u64 v[176:177], v[218:219], 0, s[20:21]
	s_addc_u32 s35, s39, 0
	s_add_i32 s38, s62, s25
	global_load_lds_dwordx4 v[176:177], off
	v_lshl_add_u64 v[176:177], s[34:35], 0, v[130:131]
	s_mov_b32 m0, s38
	s_nop 0
	global_load_lds_dwordx4 v[176:177], off
	v_lshl_add_u64 v[176:177], s[34:35], 0, v[134:135]
	s_add_i32 m0, s38, 0x2000
	s_nop 0
	global_load_lds_dwordx4 v[176:177], off
	v_lshl_add_u64 v[176:177], v[220:221], 0, s[20:21]
	s_mov_b32 m0, s51
	s_nop 0
	global_load_lds_dwordx4 v[176:177], off
	v_lshl_add_u64 v[176:177], v[222:223], 0, s[20:21]
	s_mov_b32 m0, s52
	s_nop 0
	global_load_lds_dwordx4 v[176:177], off
	s_waitcnt vmcnt(8)
	s_waitcnt lgkmcnt(0)
	s_barrier
	s_waitcnt lgkmcnt(0)
	v_mfma_f32_16x16x32_bf16 v[60:63], v[144:147], v[186:189], v[60:63]
	v_mfma_f32_16x16x32_bf16 v[56:59], v[152:155], v[186:189], v[56:59]
	v_mfma_f32_16x16x32_bf16 v[44:47], v[144:147], v[194:197], v[44:47]
	v_mfma_f32_16x16x32_bf16 v[40:43], v[152:155], v[194:197], v[40:43]
	v_mfma_f32_16x16x32_bf16 v[28:31], v[144:147], v[202:205], v[28:31]
	v_mfma_f32_16x16x32_bf16 v[24:27], v[152:155], v[202:205], v[24:27]
	v_mfma_f32_16x16x32_bf16 v[12:15], v[144:147], v[210:213], v[12:15]
	v_mfma_f32_16x16x32_bf16 v[8:11], v[152:155], v[210:213], v[8:11]
	v_mfma_f32_16x16x32_bf16 v[60:63], v[148:151], v[190:193], v[60:63]
	v_mfma_f32_16x16x32_bf16 v[56:59], v[156:159], v[190:193], v[56:59]
	v_mfma_f32_16x16x32_bf16 v[44:47], v[148:151], v[198:201], v[44:47]
	v_mfma_f32_16x16x32_bf16 v[40:43], v[156:159], v[198:201], v[40:43]
	v_mfma_f32_16x16x32_bf16 v[28:31], v[148:151], v[206:209], v[28:31]
	v_mfma_f32_16x16x32_bf16 v[24:27], v[156:159], v[206:209], v[24:27]
	v_mfma_f32_16x16x32_bf16 v[12:15], v[148:151], v[214:217], v[12:15]
	v_mfma_f32_16x16x32_bf16 v[8:11], v[156:159], v[214:217], v[8:11]
	v_mfma_f32_16x16x32_bf16 v[52:55], v[160:163], v[186:189], v[52:55]
	v_mfma_f32_16x16x32_bf16 v[48:51], v[168:171], v[186:189], v[48:51]
	v_mfma_f32_16x16x32_bf16 v[36:39], v[160:163], v[194:197], v[36:39]
	v_mfma_f32_16x16x32_bf16 v[32:35], v[168:171], v[194:197], v[32:35]
	v_mfma_f32_16x16x32_bf16 v[20:23], v[160:163], v[202:205], v[20:23]
	v_mfma_f32_16x16x32_bf16 v[16:19], v[168:171], v[202:205], v[16:19]
	v_mfma_f32_16x16x32_bf16 v[4:7], v[160:163], v[210:213], v[4:7]
	v_mfma_f32_16x16x32_bf16 v[0:3], v[168:171], v[210:213], v[0:3]
	v_mfma_f32_16x16x32_bf16 v[52:55], v[164:167], v[190:193], v[52:55]
	v_mfma_f32_16x16x32_bf16 v[48:51], v[172:175], v[190:193], v[48:51]
	v_mfma_f32_16x16x32_bf16 v[36:39], v[164:167], v[198:201], v[36:39]
	v_mfma_f32_16x16x32_bf16 v[32:35], v[172:175], v[198:201], v[32:35]
	v_mfma_f32_16x16x32_bf16 v[20:23], v[164:167], v[206:209], v[20:23]
	v_mfma_f32_16x16x32_bf16 v[16:19], v[172:175], v[206:209], v[16:19]
	v_mfma_f32_16x16x32_bf16 v[4:7], v[164:167], v[214:217], v[4:7]
	v_mfma_f32_16x16x32_bf16 v[0:3], v[172:175], v[214:217], v[0:3]
	s_barrier
	s_add_i32 s60, s60, 2
	s_add_u32 s16, s16, 0x100
	s_addc_u32 s27, s27, 0
	s_cmp_gt_u32 s60, 41
	s_mov_b64 s[34:35], s[36:37]
	s_cbranch_scc0 .LBB0_1931
	s_and_b64 vcc, exec, s[22:23]
	s_cbranch_vccz .LBB0_1934
	s_barrier
